# k48 + write-through (sc1) for the plain q/k/v/glu stores of the w_in phase
# baseline (speedup 1.0000x reference)
.LBB0_118:
	v_lshl_add_u32 v144, s66, 7, v167
	s_and_saveexec_b64 s[8:9], s[6:7]
	s_cbranch_execz .LBB0_123
	v_mul_f32_e32 v129, 0xbfb8aa3b, v112
	v_mul_f32_e32 v130, 0xbfb8aa3b, v117
	v_exp_f32_e32 v129, v129
	v_exp_f32_e32 v131, v130
	v_mul_f32_e32 v130, 0xbfb8aa3b, v113
	v_exp_f32_e32 v132, v130
	v_add_f32_e32 v129, 1.0, v129
	v_rcp_f32_e32 v130, v129
	v_add_f32_e32 v129, 1.0, v131
	v_add_f32_e32 v131, 1.0, v132
	v_mul_f32_e32 v132, 0xbfb8aa3b, v118
	v_exp_f32_e32 v132, v132
	v_mul_f32_e32 v133, 0xbfb8aa3b, v114
	v_exp_f32_e32 v133, v133
	v_mul_f32_e32 v128, 0xbfb8aa3b, v116
	v_add_f32_e32 v132, 1.0, v132
	v_rcp_f32_e32 v134, v132
	v_add_f32_e32 v132, 1.0, v133
	v_mul_f32_e32 v133, 0xbfb8aa3b, v119
	v_exp_f32_e32 v133, v133
	v_mul_f32_e32 v135, 0xbfb8aa3b, v115
	v_exp_f32_e32 v128, v128
	v_exp_f32_e32 v157, v135
	v_rcp_f32_e32 v158, v132
	v_add_f32_e32 v132, 1.0, v133
	v_add_f32_e32 v128, 1.0, v128
	v_rcp_f32_e32 v135, v132
	v_add_f32_e32 v132, 1.0, v157
	v_rcp_f32_e32 v128, v128
	v_rcp_f32_e32 v129, v129
	v_rcp_f32_e32 v131, v131
	v_rcp_f32_e32 v159, v132
	v_ashrrev_i32_e32 v157, 31, v156
	v_lshlrev_b64 v[162:163], 10, v[156:157]
	v_lshl_add_u64 v[162:163], s[42:43], 0, v[162:163]
	v_pk_mul_f32 v[132:133], v[128:129], v[124:125]
	v_pk_mul_f32 v[128:129], v[130:131], v[120:121]
	v_pk_mul_f32 v[134:135], v[134:135], v[126:127]
	v_pk_mul_f32 v[130:131], v[158:159], v[122:123]
	v_cvt_pk_bf16_f32 v158, v132, v133
	v_cvt_pk_bf16_f32 v159, v134, v135
	v_lshl_add_u64 v[162:163], v[144:145], 1, v[162:163]
	v_cvt_pk_bf16_f32 v160, v128, v129
	v_cvt_pk_bf16_f32 v161, v130, v131
	global_store_dwordx4 v[162:163], v[158:161], off nt
	v_cmp_lt_i32_e32 vcc, s77, v156
	s_nop 0
	v_mov_b64_e32 v[158:159], 0
	s_and_saveexec_b64 s[10:11], vcc
	v_add_u32_e32 v157, 0xffffc000, v156
	v_lshrrev_b32_e32 v157, 2, v157
	v_mad_u64_u32 v[158:159], s[64:65], v157, 30, v[146:147]
	v_lshlrev_b64 v[158:159], 11, v[158:159]
	v_lshl_add_u64 v[158:159], s[52:53], 0, v[158:159]
	v_lshl_add_u64 v[158:159], v[144:145], 2, v[158:159]
	s_or_b64 exec, exec, s[10:11]
	v_cmp_ne_u64_e32 vcc, 0, v[158:159]
	s_and_b64 exec, exec, vcc
	s_cbranch_execz .LBB0_123
	global_store_dwordx4 v[158:159], v[132:135], off sc1
	global_store_dwordx4 v[158:159], v[128:131], off offset:16 sc1
.LBB0_123:
	s_or_b64 exec, exec, s[8:9]
	v_or_b32_e32 v158, 16, v156
	v_cmp_gt_i32_e32 vcc, s29, v158
	s_and_saveexec_b64 s[8:9], vcc
	s_cbranch_execz .LBB0_128
	v_mul_f32_e32 v129, 0xbfb8aa3b, v96
	v_mul_f32_e32 v130, 0xbfb8aa3b, v101
	v_exp_f32_e32 v129, v129
	v_exp_f32_e32 v131, v130
	v_mul_f32_e32 v130, 0xbfb8aa3b, v97
	v_exp_f32_e32 v132, v130
	v_add_f32_e32 v129, 1.0, v129
	v_rcp_f32_e32 v130, v129
	v_add_f32_e32 v129, 1.0, v131
	v_add_f32_e32 v131, 1.0, v132
	v_mul_f32_e32 v132, 0xbfb8aa3b, v102
	v_exp_f32_e32 v132, v132
	v_mul_f32_e32 v133, 0xbfb8aa3b, v98
	v_exp_f32_e32 v133, v133
	v_mul_f32_e32 v128, 0xbfb8aa3b, v100
	v_add_f32_e32 v132, 1.0, v132
	v_rcp_f32_e32 v134, v132
	v_add_f32_e32 v132, 1.0, v133
	v_mul_f32_e32 v133, 0xbfb8aa3b, v103
	v_exp_f32_e32 v133, v133
	v_mul_f32_e32 v135, 0xbfb8aa3b, v99
	v_exp_f32_e32 v128, v128
	v_exp_f32_e32 v157, v135
	v_rcp_f32_e32 v160, v132
	v_add_f32_e32 v132, 1.0, v133
	v_add_f32_e32 v128, 1.0, v128
	v_rcp_f32_e32 v135, v132
	v_add_f32_e32 v132, 1.0, v157
	v_rcp_f32_e32 v128, v128
	v_rcp_f32_e32 v129, v129
	v_rcp_f32_e32 v131, v131
	v_rcp_f32_e32 v161, v132
	v_ashrrev_i32_e32 v159, 31, v158
	v_lshlrev_b64 v[172:173], 10, v[158:159]
	v_lshl_add_u64 v[172:173], s[42:43], 0, v[172:173]
	v_pk_mul_f32 v[132:133], v[128:129], v[108:109]
	v_pk_mul_f32 v[128:129], v[130:131], v[104:105]
	v_pk_mul_f32 v[134:135], v[134:135], v[110:111]
	v_pk_mul_f32 v[130:131], v[160:161], v[106:107]
	v_lshl_add_u64 v[172:173], v[144:145], 1, v[172:173]
	v_cmp_lt_i32_e32 vcc, s77, v158
	v_mov_b64_e32 v[158:159], 0
	v_cvt_pk_bf16_f32 v160, v132, v133
	v_cvt_pk_bf16_f32 v161, v134, v135
	v_cvt_pk_bf16_f32 v162, v128, v129
	v_cvt_pk_bf16_f32 v163, v130, v131
	global_store_dwordx4 v[172:173], v[160:163], off nt
	s_and_saveexec_b64 s[10:11], vcc
	v_add_u32_e32 v157, 0xffffc010, v156
	v_lshrrev_b32_e32 v157, 2, v157
	v_mad_u64_u32 v[158:159], s[64:65], v157, 30, v[146:147]
	v_lshlrev_b64 v[158:159], 11, v[158:159]
	v_lshl_add_u64 v[158:159], s[52:53], 0, v[158:159]
	v_lshl_add_u64 v[158:159], v[144:145], 2, v[158:159]
	s_or_b64 exec, exec, s[10:11]
	v_cmp_ne_u64_e32 vcc, 0, v[158:159]
	s_and_b64 exec, exec, vcc
	s_cbranch_execz .LBB0_128
	global_store_dwordx4 v[158:159], v[132:135], off sc1
	global_store_dwordx4 v[158:159], v[128:131], off offset:16 sc1

.LBB0_132:
	global_store_dwordx4 v[160:161], v[132:135], off sc1
	global_store_dwordx4 v[160:161], v[128:131], off offset:16 sc1

.LBB0_138:
	s_or_b64 exec, exec, s[10:11]
	v_add_u32_e32 v158, 0x80, v156
	v_cmp_gt_i32_e32 vcc, s87, v156
	s_and_saveexec_b64 s[8:9], vcc
	s_cbranch_execz .LBB0_143
	v_mul_f32_e32 v129, 0xbfb8aa3b, v48
	v_mul_f32_e32 v130, 0xbfb8aa3b, v53
	v_exp_f32_e32 v129, v129
	v_exp_f32_e32 v131, v130
	v_mul_f32_e32 v130, 0xbfb8aa3b, v49
	v_exp_f32_e32 v132, v130
	v_add_f32_e32 v129, 1.0, v129
	v_rcp_f32_e32 v130, v129
	v_add_f32_e32 v129, 1.0, v131
	v_add_f32_e32 v131, 1.0, v132
	v_mul_f32_e32 v132, 0xbfb8aa3b, v54
	v_exp_f32_e32 v132, v132
	v_mul_f32_e32 v133, 0xbfb8aa3b, v50
	v_exp_f32_e32 v133, v133
	v_mul_f32_e32 v128, 0xbfb8aa3b, v52
	v_add_f32_e32 v132, 1.0, v132
	v_rcp_f32_e32 v134, v132
	v_add_f32_e32 v132, 1.0, v133
	v_mul_f32_e32 v133, 0xbfb8aa3b, v55
	v_exp_f32_e32 v133, v133
	v_mul_f32_e32 v135, 0xbfb8aa3b, v51
	v_exp_f32_e32 v128, v128
	v_exp_f32_e32 v157, v135
	v_rcp_f32_e32 v160, v132
	v_add_f32_e32 v132, 1.0, v133
	v_add_f32_e32 v128, 1.0, v128
	v_rcp_f32_e32 v135, v132
	v_add_f32_e32 v132, 1.0, v157
	v_rcp_f32_e32 v128, v128
	v_rcp_f32_e32 v129, v129
	v_rcp_f32_e32 v131, v131
	v_rcp_f32_e32 v161, v132
	v_ashrrev_i32_e32 v159, 31, v158
	v_lshlrev_b64 v[172:173], 10, v[158:159]
	v_lshl_add_u64 v[172:173], s[42:43], 0, v[172:173]
	v_pk_mul_f32 v[132:133], v[128:129], v[60:61]
	v_pk_mul_f32 v[128:129], v[130:131], v[56:57]
	v_pk_mul_f32 v[134:135], v[134:135], v[62:63]
	v_pk_mul_f32 v[130:131], v[160:161], v[58:59]
	v_cvt_pk_bf16_f32 v160, v132, v133
	v_cvt_pk_bf16_f32 v161, v134, v135
	v_lshl_add_u64 v[172:173], v[144:145], 1, v[172:173]
	v_cvt_pk_bf16_f32 v162, v128, v129
	v_cvt_pk_bf16_f32 v163, v130, v131
	global_store_dwordx4 v[172:173], v[160:163], off nt
	v_cmp_lt_i32_e32 vcc, s31, v156
	s_nop 0
	v_mov_b64_e32 v[160:161], 0
	s_and_saveexec_b64 s[10:11], vcc
	v_add_u32_e32 v157, 0xffffc080, v156
	v_lshrrev_b32_e32 v157, 2, v157
	v_mad_u64_u32 v[160:161], s[24:25], v157, 30, v[146:147]
	v_lshlrev_b64 v[160:161], 11, v[160:161]
	v_lshl_add_u64 v[160:161], s[52:53], 0, v[160:161]
	v_lshl_add_u64 v[160:161], v[144:145], 2, v[160:161]
	s_or_b64 exec, exec, s[10:11]
	v_cmp_ne_u64_e32 vcc, 0, v[160:161]
	s_and_b64 exec, exec, vcc
	s_cbranch_execz .LBB0_143
	global_store_dwordx4 v[160:161], v[132:135], off sc1
	global_store_dwordx4 v[160:161], v[128:131], off offset:16 sc1
.LBB0_143:
	s_or_b64 exec, exec, s[8:9]
	v_cmp_gt_i32_e32 vcc, s26, v156
	s_and_saveexec_b64 s[8:9], vcc
	s_cbranch_execz .LBB0_148
	v_mul_f32_e32 v129, 0xbfb8aa3b, v32
	v_mul_f32_e32 v130, 0xbfb8aa3b, v37
	v_exp_f32_e32 v129, v129
	v_exp_f32_e32 v131, v130
	v_mul_f32_e32 v130, 0xbfb8aa3b, v33
	v_exp_f32_e32 v132, v130
	v_add_f32_e32 v129, 1.0, v129
	v_rcp_f32_e32 v130, v129
	v_add_f32_e32 v129, 1.0, v131
	v_add_f32_e32 v131, 1.0, v132
	v_mul_f32_e32 v132, 0xbfb8aa3b, v38
	v_exp_f32_e32 v132, v132
	v_mul_f32_e32 v133, 0xbfb8aa3b, v34
	v_exp_f32_e32 v133, v133
	v_mul_f32_e32 v128, 0xbfb8aa3b, v36
	v_add_f32_e32 v132, 1.0, v132
	v_rcp_f32_e32 v134, v132
	v_add_f32_e32 v132, 1.0, v133
	v_mul_f32_e32 v133, 0xbfb8aa3b, v39
	v_exp_f32_e32 v133, v133
	v_mul_f32_e32 v135, 0xbfb8aa3b, v35
	v_exp_f32_e32 v128, v128
	v_exp_f32_e32 v157, v135
	v_rcp_f32_e32 v160, v132
	v_add_f32_e32 v132, 1.0, v133
	v_add_f32_e32 v128, 1.0, v128
	v_rcp_f32_e32 v135, v132
	v_add_f32_e32 v132, 1.0, v157
	v_ashrrev_i32_e32 v157, 31, v156
	v_rcp_f32_e32 v128, v128
	v_rcp_f32_e32 v129, v129
	v_rcp_f32_e32 v131, v131
	v_rcp_f32_e32 v161, v132
	v_lshlrev_b64 v[172:173], 10, v[156:157]
	v_lshl_add_u64 v[172:173], s[42:43], 0, v[172:173]
	v_lshl_add_u64 v[172:173], v[144:145], 1, v[172:173]
	v_add_co_u32_e32 v172, vcc, 0x24000, v172
	v_pk_mul_f32 v[132:133], v[128:129], v[44:45]
	v_pk_mul_f32 v[128:129], v[130:131], v[40:41]
	v_pk_mul_f32 v[134:135], v[134:135], v[46:47]
	v_pk_mul_f32 v[130:131], v[160:161], v[42:43]
	v_cvt_pk_bf16_f32 v160, v132, v133
	v_cvt_pk_bf16_f32 v161, v134, v135
	v_addc_co_u32_e32 v173, vcc, 0, v173, vcc
	v_cvt_pk_bf16_f32 v162, v128, v129
	v_cvt_pk_bf16_f32 v163, v130, v131
	global_store_dwordx4 v[172:173], v[160:163], off nt
	v_cmp_lt_i32_e32 vcc, s27, v156
	s_nop 0
	v_mov_b64_e32 v[160:161], 0
	s_and_saveexec_b64 s[10:11], vcc
	v_add_u32_e32 v157, 0xffffc090, v156
	v_lshrrev_b32_e32 v157, 2, v157
	v_mad_u64_u32 v[160:161], s[24:25], v157, 30, v[146:147]
	v_lshlrev_b64 v[160:161], 11, v[160:161]
	v_lshl_add_u64 v[160:161], s[52:53], 0, v[160:161]
	v_lshl_add_u64 v[160:161], v[144:145], 2, v[160:161]
	s_or_b64 exec, exec, s[10:11]
	v_cmp_ne_u64_e32 vcc, 0, v[160:161]
	s_and_b64 exec, exec, vcc
	s_cbranch_execz .LBB0_148
	global_store_dwordx4 v[160:161], v[132:135], off sc1
	global_store_dwordx4 v[160:161], v[128:131], off offset:16 sc1

.LBB0_152:
	global_store_dwordx4 v[162:163], v[132:135], off sc1
	global_store_dwordx4 v[162:163], v[128:131], off offset:16 sc1

.LBB0_159:
	s_lshl_b32 s8, s66, 8
	s_and_b32 s8, s8, 0x100
	s_cmp_gt_u32 s66, 1
	v_or_b32_e32 v158, s8, v166
	s_cselect_b64 s[10:11], -1, 0
	s_and_b32 s8, s66, -2
	s_cmp_eq_u32 s8, 2
	s_cselect_b64 s[64:65], -1, 0
	s_and_b64 s[8:9], s[64:65], exec
	s_mov_b32 s8, 0x203e000
	s_cselect_b32 s72, s8, 0x204e000
	s_mov_b32 s8, 0x1020000
	s_cselect_b32 s24, s8, 0x1820000
	s_and_saveexec_b64 s[66:67], s[6:7]
	s_cbranch_execz .LBB0_184
	v_ashrrev_i32_e32 v157, 31, v156
	v_add_u32_e32 v144, 0xffffc000, v156
	v_lshlrev_b64 v[130:131], 9, v[156:157]
	v_cmp_gt_i32_e64 s[8:9], s87, v156
	v_lshlrev_b64 v[128:129], 11, v[144:145]
	v_cmp_lt_i32_e64 s[6:7], s77, v156
	s_and_b64 vcc, exec, s[10:11]
	s_cbranch_vccz .LBB0_170
	s_and_b64 s[68:69], s[64:65], exec
	s_cselect_b32 s25, s89, s91
	s_cselect_b32 s68, s88, s90
	v_mov_b32_e32 v160, s68
	v_mov_b32_e32 v161, s25
	s_lshl_b32 s25, s24, 2
	v_lshl_add_u64 v[160:161], v[130:131], 1, v[160:161]
	v_lshlrev_b32_e32 v144, 1, v158
	s_add_u32 s68, s16, s25
	v_cvt_pk_bf16_f32 v132, v124, v125
	v_cvt_pk_bf16_f32 v133, v126, v127
	v_lshl_add_u64 v[160:161], v[160:161], 0, v[144:145]
	s_addc_u32 s69, s17, 0
	s_lshl_b32 s25, s72, 2
	v_cvt_pk_bf16_f32 v134, v120, v121
	v_cvt_pk_bf16_f32 v135, v122, v123
	global_store_dwordx4 v[160:161], v[132:135], off nt
	v_lshlrev_b32_e32 v144, 2, v158
	s_nop 0
	v_lshl_add_u64 v[132:133], v[130:131], 2, s[68:69]
	s_add_u32 s68, s16, s25
	s_addc_u32 s69, s17, 0
	v_lshl_add_u64 v[134:135], s[68:69], 0, v[128:129]
	v_cndmask_b32_e64 v133, v135, v133, s[8:9]
	v_cndmask_b32_e64 v132, v134, v132, s[8:9]
	v_lshl_add_u64 v[134:135], v[132:133], 0, v[144:145]
	global_store_dwordx4 v[134:135], v[124:127], off sc1
	s_mov_b64 s[68:69], -1
	v_lshlrev_b64 v[132:133], 10, v[156:157]
	v_lshl_add_u64 v[132:133], s[40:41], 0, v[132:133]
	s_cbranch_execz .LBB0_171
	s_branch .LBB0_174

.LBB0_171:
	v_lshlrev_b32_e32 v144, 1, v158
	v_pk_mul_f32 v[126:127], v[126:127], s[56:57] op_sel_hi:[1,0]
	v_pk_mul_f32 v[124:125], v[124:125], s[56:57] op_sel_hi:[1,0]
	v_pk_mul_f32 v[122:123], v[122:123], s[56:57] op_sel_hi:[1,0]
	v_pk_mul_f32 v[120:121], v[120:121], s[56:57] op_sel_hi:[1,0]
	v_lshl_add_u64 v[134:135], v[132:133], 0, v[144:145]
	v_cvt_pk_bf16_f32 v160, v124, v125
	v_cvt_pk_bf16_f32 v161, v126, v127
	v_cvt_pk_bf16_f32 v162, v120, v121
	v_cvt_pk_bf16_f32 v163, v122, v123
	global_store_dwordx4 v[134:135], v[160:163], off nt
	s_and_saveexec_b64 s[70:71], s[6:7]
	s_cbranch_execz .LBB0_173
	v_lshl_add_u64 v[134:135], s[44:45], 0, v[128:129]
	v_lshlrev_b32_e32 v144, 2, v158
	v_lshl_add_u64 v[134:135], v[134:135], 0, v[144:145]
	s_or_b64 s[68:69], s[68:69], exec
	global_store_dwordx4 v[134:135], v[124:127], off sc1

.LBB0_176:
	s_and_b64 s[68:69], s[64:65], exec
	s_cselect_b32 s25, s89, s91
	s_cselect_b32 s68, s88, s90
	v_mov_b32_e32 v124, s68
	v_mov_b32_e32 v125, s25
	s_lshl_b32 s25, s24, 2
	v_lshl_add_u64 v[124:125], v[130:131], 1, v[124:125]
	v_lshlrev_b32_e32 v144, 1, v158
	s_add_u32 s68, s16, s25
	v_cvt_pk_bf16_f32 v120, v116, v117
	v_cvt_pk_bf16_f32 v121, v118, v119
	v_lshl_add_u64 v[124:125], v[124:125], 0, v[144:145]
	s_addc_u32 s69, s17, 0
	s_lshl_b32 s25, s72, 2
	v_cvt_pk_bf16_f32 v122, v112, v113
	v_cvt_pk_bf16_f32 v123, v114, v115
	global_store_dwordx4 v[124:125], v[120:123], off offset:256 nt
	v_lshlrev_b32_e32 v144, 2, v158
	s_nop 0
	v_lshl_add_u64 v[120:121], v[130:131], 2, s[68:69]
	s_add_u32 s68, s16, s25
	s_addc_u32 s69, s17, 0
	v_lshl_add_u64 v[122:123], s[68:69], 0, v[128:129]
	v_cndmask_b32_e64 v121, v123, v121, s[8:9]
	v_cndmask_b32_e64 v120, v122, v120, s[8:9]
	v_lshl_add_u64 v[122:123], v[120:121], 0, v[144:145]
	v_lshl_add_u64 v[120:121], v[122:123], 0, s[58:59]
	s_mov_b64 s[8:9], -1
	global_store_dwordx4 v[122:123], v[116:119], off offset:512 sc1
	s_cbranch_execz .LBB0_179
	s_branch .LBB0_182
.LBB0_177:
	global_store_dwordx4 v[134:135], v[120:123], off offset:16 sc1
	s_or_b64 exec, exec, s[70:71]
	s_andn2_b64 vcc, exec, s[10:11]
	s_cbranch_vccz .LBB0_176

.LBB0_179:
	v_lshlrev_b32_e32 v144, 1, v158
	v_pk_mul_f32 v[118:119], v[118:119], s[56:57] op_sel_hi:[1,0]
	v_pk_mul_f32 v[116:117], v[116:117], s[56:57] op_sel_hi:[1,0]
	v_pk_mul_f32 v[114:115], v[114:115], s[56:57] op_sel_hi:[1,0]
	v_pk_mul_f32 v[112:113], v[112:113], s[56:57] op_sel_hi:[1,0]
	v_cvt_pk_bf16_f32 v120, v116, v117
	v_cvt_pk_bf16_f32 v121, v118, v119
	v_lshl_add_u64 v[124:125], v[132:133], 0, v[144:145]
	v_cvt_pk_bf16_f32 v122, v112, v113
	v_cvt_pk_bf16_f32 v123, v114, v115
	global_store_dwordx4 v[124:125], v[120:123], off offset:256 nt
	s_and_saveexec_b64 s[68:69], s[6:7]
	s_cbranch_execz .LBB0_181
	v_lshl_add_u64 v[120:121], s[44:45], 0, v[128:129]
	v_lshlrev_b32_e32 v144, 2, v158
	v_lshl_add_u64 v[122:123], v[120:121], 0, v[144:145]
	v_lshl_add_u64 v[120:121], v[122:123], 0, s[58:59]
	s_or_b64 s[8:9], s[8:9], exec
	global_store_dwordx4 v[122:123], v[116:119], off offset:512 sc1

.LBB0_182:
	s_and_b64 exec, exec, s[8:9]
	s_cbranch_execz .LBB0_184
	global_store_dwordx4 v[120:121], v[112:115], off offset:16 sc1
.LBB0_184:
	s_or_b64 exec, exec, s[66:67]
	v_or_b32_e32 v116, 16, v156
	v_cndmask_b32_e64 v112, 0, 1, s[10:11]
	v_cmp_gt_i32_e32 vcc, s29, v116
	v_cmp_ne_u32_e64 s[6:7], 1, v112
	s_and_saveexec_b64 s[66:67], vcc
	s_cbranch_execz .LBB0_201
	v_ashrrev_i32_e32 v117, 31, v116
	v_add_u32_e32 v144, 0xffffc010, v156
	v_lshlrev_b64 v[114:115], 9, v[116:117]
	v_cmp_gt_i32_e64 s[10:11], s87, v116
	v_lshlrev_b64 v[112:113], 11, v[144:145]
	s_and_b64 vcc, exec, s[6:7]
	v_cmp_lt_i32_e64 s[8:9], s77, v116
	s_cbranch_vccnz .LBB0_187
	s_and_b64 s[68:69], s[64:65], exec
	s_cselect_b32 s25, s89, s91
	s_cselect_b32 s68, s88, s90
	v_mov_b32_e32 v122, s68
	v_mov_b32_e32 v123, s25
	s_lshl_b32 s25, s24, 2
	v_lshl_add_u64 v[122:123], v[114:115], 1, v[122:123]
	v_lshlrev_b32_e32 v144, 1, v158
	s_add_u32 s68, s16, s25
	v_cvt_pk_bf16_f32 v118, v108, v109
	v_cvt_pk_bf16_f32 v119, v110, v111
	v_lshl_add_u64 v[122:123], v[122:123], 0, v[144:145]
	s_addc_u32 s69, s17, 0
	s_lshl_b32 s25, s72, 2
	v_cvt_pk_bf16_f32 v120, v104, v105
	v_cvt_pk_bf16_f32 v121, v106, v107
	global_store_dwordx4 v[122:123], v[118:121], off nt
	v_lshlrev_b32_e32 v144, 2, v158
	s_nop 0
	v_lshl_add_u64 v[118:119], v[114:115], 2, s[68:69]
	s_add_u32 s68, s16, s25
	s_addc_u32 s69, s17, 0
	v_lshl_add_u64 v[120:121], s[68:69], 0, v[112:113]
	v_cndmask_b32_e64 v119, v121, v119, s[10:11]
	v_cndmask_b32_e64 v118, v120, v118, s[10:11]
	v_lshl_add_u64 v[118:119], v[118:119], 0, v[144:145]
	s_mov_b64 s[68:69], -1
	global_store_dwordx4 v[118:119], v[108:111], off sc1
	v_lshlrev_b64 v[116:117], 10, v[116:117]
	v_lshl_add_u64 v[116:117], s[40:41], 0, v[116:117]
	s_cbranch_execz .LBB0_188
	s_branch .LBB0_191

.LBB0_188:
	v_lshlrev_b32_e32 v144, 1, v158
	v_pk_mul_f32 v[110:111], v[110:111], s[56:57] op_sel_hi:[1,0]
	v_pk_mul_f32 v[108:109], v[108:109], s[56:57] op_sel_hi:[1,0]
	v_pk_mul_f32 v[106:107], v[106:107], s[56:57] op_sel_hi:[1,0]
	v_pk_mul_f32 v[104:105], v[104:105], s[56:57] op_sel_hi:[1,0]
	v_cvt_pk_bf16_f32 v118, v108, v109
	v_cvt_pk_bf16_f32 v119, v110, v111
	v_lshl_add_u64 v[122:123], v[116:117], 0, v[144:145]
	v_cvt_pk_bf16_f32 v120, v104, v105
	v_cvt_pk_bf16_f32 v121, v106, v107
	global_store_dwordx4 v[122:123], v[118:121], off nt
	s_and_saveexec_b64 s[70:71], s[8:9]
	s_cbranch_execz .LBB0_190
	v_lshl_add_u64 v[118:119], s[44:45], 0, v[112:113]
	v_lshlrev_b32_e32 v144, 2, v158
	v_lshl_add_u64 v[118:119], v[118:119], 0, v[144:145]
	s_or_b64 s[68:69], s[68:69], exec
	global_store_dwordx4 v[118:119], v[108:111], off sc1

.LBB0_193:
	s_and_b64 s[68:69], s[64:65], exec
	s_cselect_b32 s25, s89, s91
	s_cselect_b32 s68, s88, s90
	v_mov_b32_e32 v108, s68
	v_mov_b32_e32 v109, s25
	s_lshl_b32 s25, s24, 2
	v_lshl_add_u64 v[108:109], v[114:115], 1, v[108:109]
	v_lshlrev_b32_e32 v144, 1, v158
	s_add_u32 s68, s16, s25
	v_cvt_pk_bf16_f32 v104, v100, v101
	v_cvt_pk_bf16_f32 v105, v102, v103
	v_lshl_add_u64 v[108:109], v[108:109], 0, v[144:145]
	s_addc_u32 s69, s17, 0
	s_lshl_b32 s25, s72, 2
	v_cvt_pk_bf16_f32 v106, v96, v97
	v_cvt_pk_bf16_f32 v107, v98, v99
	global_store_dwordx4 v[108:109], v[104:107], off offset:256 nt
	v_lshlrev_b32_e32 v144, 2, v158
	s_nop 0
	v_lshl_add_u64 v[104:105], v[114:115], 2, s[68:69]
	s_add_u32 s68, s16, s25
	s_addc_u32 s69, s17, 0
	v_lshl_add_u64 v[106:107], s[68:69], 0, v[112:113]
	v_cndmask_b32_e64 v105, v107, v105, s[10:11]
	v_cndmask_b32_e64 v104, v106, v104, s[10:11]
	v_lshl_add_u64 v[106:107], v[104:105], 0, v[144:145]
	v_lshl_add_u64 v[104:105], v[106:107], 0, s[58:59]
	s_mov_b64 s[10:11], -1
	global_store_dwordx4 v[106:107], v[100:103], off offset:512 sc1
	s_cbranch_execz .LBB0_196
	s_branch .LBB0_199
.LBB0_194:
	global_store_dwordx4 v[118:119], v[104:107], off offset:16 sc1
	s_or_b64 exec, exec, s[70:71]
	s_and_b64 vcc, exec, s[6:7]
	s_cbranch_vccz .LBB0_193

.LBB0_196:
	v_lshlrev_b32_e32 v144, 1, v158
	v_pk_mul_f32 v[102:103], v[102:103], s[56:57] op_sel_hi:[1,0]
	v_pk_mul_f32 v[100:101], v[100:101], s[56:57] op_sel_hi:[1,0]
	v_pk_mul_f32 v[98:99], v[98:99], s[56:57] op_sel_hi:[1,0]
	v_pk_mul_f32 v[96:97], v[96:97], s[56:57] op_sel_hi:[1,0]
	v_cvt_pk_bf16_f32 v104, v100, v101
	v_cvt_pk_bf16_f32 v105, v102, v103
	v_lshl_add_u64 v[108:109], v[116:117], 0, v[144:145]
	v_cvt_pk_bf16_f32 v106, v96, v97
	v_cvt_pk_bf16_f32 v107, v98, v99
	global_store_dwordx4 v[108:109], v[104:107], off offset:256 nt
	s_and_saveexec_b64 s[68:69], s[8:9]
	s_cbranch_execz .LBB0_198
	v_lshl_add_u64 v[104:105], s[44:45], 0, v[112:113]
	v_lshlrev_b32_e32 v144, 2, v158
	v_lshl_add_u64 v[106:107], v[104:105], 0, v[144:145]
	v_lshl_add_u64 v[104:105], v[106:107], 0, s[58:59]
	s_or_b64 s[10:11], s[10:11], exec
	global_store_dwordx4 v[106:107], v[100:103], off offset:512 sc1

.LBB0_199:
	s_and_b64 exec, exec, s[10:11]
	s_cbranch_execz .LBB0_201
	global_store_dwordx4 v[104:105], v[96:99], off offset:16 sc1
.LBB0_201:
	s_or_b64 exec, exec, s[66:67]
	v_or_b32_e32 v100, 32, v156
	v_cmp_gt_i32_e32 vcc, s29, v100
	s_and_saveexec_b64 s[66:67], vcc
	s_cbranch_execz .LBB0_218
	v_ashrrev_i32_e32 v101, 31, v100
	v_add_u32_e32 v144, 0xffffc020, v156
	v_lshlrev_b64 v[98:99], 9, v[100:101]
	v_cmp_gt_i32_e64 s[10:11], s87, v100
	v_lshlrev_b64 v[96:97], 11, v[144:145]
	s_and_b64 vcc, exec, s[6:7]
	v_cmp_lt_i32_e64 s[8:9], s77, v100
	s_cbranch_vccnz .LBB0_204
	s_and_b64 s[68:69], s[64:65], exec
	s_cselect_b32 s25, s89, s91
	s_cselect_b32 s68, s88, s90
	v_mov_b32_e32 v106, s68
	v_mov_b32_e32 v107, s25
	s_lshl_b32 s25, s24, 2
	v_lshl_add_u64 v[106:107], v[98:99], 1, v[106:107]
	v_lshlrev_b32_e32 v144, 1, v158
	s_add_u32 s68, s16, s25
	v_cvt_pk_bf16_f32 v102, v92, v93
	v_cvt_pk_bf16_f32 v103, v94, v95
	v_lshl_add_u64 v[106:107], v[106:107], 0, v[144:145]
	s_addc_u32 s69, s17, 0
	s_lshl_b32 s25, s72, 2
	v_cvt_pk_bf16_f32 v104, v88, v89
	v_cvt_pk_bf16_f32 v105, v90, v91
	global_store_dwordx4 v[106:107], v[102:105], off nt
	v_lshlrev_b32_e32 v144, 2, v158
	s_nop 0
	v_lshl_add_u64 v[102:103], v[98:99], 2, s[68:69]
	s_add_u32 s68, s16, s25
	s_addc_u32 s69, s17, 0
	v_lshl_add_u64 v[104:105], s[68:69], 0, v[96:97]
	v_cndmask_b32_e64 v103, v105, v103, s[10:11]
	v_cndmask_b32_e64 v102, v104, v102, s[10:11]
	v_lshl_add_u64 v[102:103], v[102:103], 0, v[144:145]
	s_mov_b64 s[68:69], -1
	global_store_dwordx4 v[102:103], v[92:95], off sc1
	v_lshlrev_b64 v[100:101], 10, v[100:101]
	v_lshl_add_u64 v[100:101], s[40:41], 0, v[100:101]
	s_cbranch_execz .LBB0_205
	s_branch .LBB0_208

.LBB0_205:
	v_lshlrev_b32_e32 v144, 1, v158
	v_pk_mul_f32 v[94:95], v[94:95], s[56:57] op_sel_hi:[1,0]
	v_pk_mul_f32 v[92:93], v[92:93], s[56:57] op_sel_hi:[1,0]
	v_pk_mul_f32 v[90:91], v[90:91], s[56:57] op_sel_hi:[1,0]
	v_pk_mul_f32 v[88:89], v[88:89], s[56:57] op_sel_hi:[1,0]
	v_cvt_pk_bf16_f32 v102, v92, v93
	v_cvt_pk_bf16_f32 v103, v94, v95
	v_lshl_add_u64 v[106:107], v[100:101], 0, v[144:145]
	v_cvt_pk_bf16_f32 v104, v88, v89
	v_cvt_pk_bf16_f32 v105, v90, v91
	global_store_dwordx4 v[106:107], v[102:105], off nt
	s_and_saveexec_b64 s[70:71], s[8:9]
	s_cbranch_execz .LBB0_207
	v_lshl_add_u64 v[102:103], s[44:45], 0, v[96:97]
	v_lshlrev_b32_e32 v144, 2, v158
	v_lshl_add_u64 v[102:103], v[102:103], 0, v[144:145]
	s_or_b64 s[68:69], s[68:69], exec
	global_store_dwordx4 v[102:103], v[92:95], off sc1

.LBB0_210:
	s_and_b64 s[68:69], s[64:65], exec
	s_cselect_b32 s25, s89, s91
	s_cselect_b32 s68, s88, s90
	v_mov_b32_e32 v92, s68
	v_mov_b32_e32 v93, s25
	s_lshl_b32 s25, s24, 2
	v_lshl_add_u64 v[92:93], v[98:99], 1, v[92:93]
	v_lshlrev_b32_e32 v144, 1, v158
	s_add_u32 s68, s16, s25
	v_cvt_pk_bf16_f32 v88, v84, v85
	v_cvt_pk_bf16_f32 v89, v86, v87
	v_lshl_add_u64 v[92:93], v[92:93], 0, v[144:145]
	s_addc_u32 s69, s17, 0
	s_lshl_b32 s25, s72, 2
	v_cvt_pk_bf16_f32 v90, v80, v81
	v_cvt_pk_bf16_f32 v91, v82, v83
	global_store_dwordx4 v[92:93], v[88:91], off offset:256 nt
	v_lshlrev_b32_e32 v144, 2, v158
	s_nop 0
	v_lshl_add_u64 v[88:89], v[98:99], 2, s[68:69]
	s_add_u32 s68, s16, s25
	s_addc_u32 s69, s17, 0
	v_lshl_add_u64 v[90:91], s[68:69], 0, v[96:97]
	v_cndmask_b32_e64 v89, v91, v89, s[10:11]
	v_cndmask_b32_e64 v88, v90, v88, s[10:11]
	v_lshl_add_u64 v[90:91], v[88:89], 0, v[144:145]
	v_lshl_add_u64 v[88:89], v[90:91], 0, s[58:59]
	s_mov_b64 s[10:11], -1
	global_store_dwordx4 v[90:91], v[84:87], off offset:512 sc1
	s_cbranch_execz .LBB0_213
	s_branch .LBB0_216
.LBB0_211:
	global_store_dwordx4 v[102:103], v[88:91], off offset:16 sc1
	s_or_b64 exec, exec, s[70:71]
	s_and_b64 vcc, exec, s[6:7]
	s_cbranch_vccz .LBB0_210

.LBB0_213:
	v_lshlrev_b32_e32 v144, 1, v158
	v_pk_mul_f32 v[86:87], v[86:87], s[56:57] op_sel_hi:[1,0]
	v_pk_mul_f32 v[84:85], v[84:85], s[56:57] op_sel_hi:[1,0]
	v_pk_mul_f32 v[82:83], v[82:83], s[56:57] op_sel_hi:[1,0]
	v_pk_mul_f32 v[80:81], v[80:81], s[56:57] op_sel_hi:[1,0]
	v_cvt_pk_bf16_f32 v88, v84, v85
	v_cvt_pk_bf16_f32 v89, v86, v87
	v_lshl_add_u64 v[92:93], v[100:101], 0, v[144:145]
	v_cvt_pk_bf16_f32 v90, v80, v81
	v_cvt_pk_bf16_f32 v91, v82, v83
	global_store_dwordx4 v[92:93], v[88:91], off offset:256 nt
	s_and_saveexec_b64 s[68:69], s[8:9]
	s_cbranch_execz .LBB0_215
	v_lshl_add_u64 v[88:89], s[44:45], 0, v[96:97]
	v_lshlrev_b32_e32 v144, 2, v158
	v_lshl_add_u64 v[90:91], v[88:89], 0, v[144:145]
	v_lshl_add_u64 v[88:89], v[90:91], 0, s[58:59]
	s_or_b64 s[10:11], s[10:11], exec
	global_store_dwordx4 v[90:91], v[84:87], off offset:512 sc1

.LBB0_216:
	s_and_b64 exec, exec, s[10:11]
	s_cbranch_execz .LBB0_218
	global_store_dwordx4 v[88:89], v[80:83], off offset:16 sc1
.LBB0_218:
	s_or_b64 exec, exec, s[66:67]
	v_or_b32_e32 v84, 48, v156
	v_cmp_gt_i32_e32 vcc, s29, v84
	s_and_saveexec_b64 s[66:67], vcc
	s_cbranch_execz .LBB0_235
	v_ashrrev_i32_e32 v85, 31, v84
	v_add_u32_e32 v144, 0xffffc030, v156
	v_lshlrev_b64 v[82:83], 9, v[84:85]
	v_cmp_gt_i32_e64 s[10:11], s87, v84
	v_lshlrev_b64 v[80:81], 11, v[144:145]
	s_and_b64 vcc, exec, s[6:7]
	v_cmp_lt_i32_e64 s[8:9], s77, v84
	s_cbranch_vccnz .LBB0_221
	s_and_b64 s[68:69], s[64:65], exec
	s_cselect_b32 s25, s89, s91
	s_cselect_b32 s68, s88, s90
	v_mov_b32_e32 v90, s68
	v_mov_b32_e32 v91, s25
	s_lshl_b32 s25, s24, 2
	v_lshl_add_u64 v[90:91], v[82:83], 1, v[90:91]
	v_lshlrev_b32_e32 v144, 1, v158
	s_add_u32 s68, s16, s25
	v_cvt_pk_bf16_f32 v86, v76, v77
	v_cvt_pk_bf16_f32 v87, v78, v79
	v_lshl_add_u64 v[90:91], v[90:91], 0, v[144:145]
	s_addc_u32 s69, s17, 0
	s_lshl_b32 s25, s72, 2
	v_cvt_pk_bf16_f32 v88, v72, v73
	v_cvt_pk_bf16_f32 v89, v74, v75
	global_store_dwordx4 v[90:91], v[86:89], off nt
	v_lshlrev_b32_e32 v144, 2, v158
	s_nop 0
	v_lshl_add_u64 v[86:87], v[82:83], 2, s[68:69]
	s_add_u32 s68, s16, s25
	s_addc_u32 s69, s17, 0
	v_lshl_add_u64 v[88:89], s[68:69], 0, v[80:81]
	v_cndmask_b32_e64 v87, v89, v87, s[10:11]
	v_cndmask_b32_e64 v86, v88, v86, s[10:11]
	v_lshl_add_u64 v[86:87], v[86:87], 0, v[144:145]
	s_mov_b64 s[68:69], -1
	global_store_dwordx4 v[86:87], v[76:79], off sc1
	v_lshlrev_b64 v[84:85], 10, v[84:85]
	v_lshl_add_u64 v[84:85], s[40:41], 0, v[84:85]
	s_cbranch_execz .LBB0_222
	s_branch .LBB0_225

.LBB0_222:
	v_lshlrev_b32_e32 v144, 1, v158
	v_pk_mul_f32 v[78:79], v[78:79], s[56:57] op_sel_hi:[1,0]
	v_pk_mul_f32 v[76:77], v[76:77], s[56:57] op_sel_hi:[1,0]
	v_pk_mul_f32 v[74:75], v[74:75], s[56:57] op_sel_hi:[1,0]
	v_pk_mul_f32 v[72:73], v[72:73], s[56:57] op_sel_hi:[1,0]
	v_cvt_pk_bf16_f32 v86, v76, v77
	v_cvt_pk_bf16_f32 v87, v78, v79
	v_lshl_add_u64 v[90:91], v[84:85], 0, v[144:145]
	v_cvt_pk_bf16_f32 v88, v72, v73
	v_cvt_pk_bf16_f32 v89, v74, v75
	global_store_dwordx4 v[90:91], v[86:89], off nt
	s_and_saveexec_b64 s[70:71], s[8:9]
	s_cbranch_execz .LBB0_224
	v_lshl_add_u64 v[86:87], s[44:45], 0, v[80:81]
	v_lshlrev_b32_e32 v144, 2, v158
	v_lshl_add_u64 v[86:87], v[86:87], 0, v[144:145]
	s_or_b64 s[68:69], s[68:69], exec
	global_store_dwordx4 v[86:87], v[76:79], off sc1

.LBB0_227:
	s_and_b64 s[68:69], s[64:65], exec
	s_cselect_b32 s25, s89, s91
	s_cselect_b32 s68, s88, s90
	v_mov_b32_e32 v76, s68
	v_mov_b32_e32 v77, s25
	s_lshl_b32 s25, s24, 2
	v_lshl_add_u64 v[76:77], v[82:83], 1, v[76:77]
	v_lshlrev_b32_e32 v144, 1, v158
	s_add_u32 s68, s16, s25
	v_cvt_pk_bf16_f32 v72, v68, v69
	v_cvt_pk_bf16_f32 v73, v70, v71
	v_lshl_add_u64 v[76:77], v[76:77], 0, v[144:145]
	s_addc_u32 s69, s17, 0
	s_lshl_b32 s25, s72, 2
	v_cvt_pk_bf16_f32 v74, v64, v65
	v_cvt_pk_bf16_f32 v75, v66, v67
	global_store_dwordx4 v[76:77], v[72:75], off offset:256 nt
	v_lshlrev_b32_e32 v144, 2, v158
	s_nop 0
	v_lshl_add_u64 v[72:73], v[82:83], 2, s[68:69]
	s_add_u32 s68, s16, s25
	s_addc_u32 s69, s17, 0
	v_lshl_add_u64 v[74:75], s[68:69], 0, v[80:81]
	v_cndmask_b32_e64 v73, v75, v73, s[10:11]
	v_cndmask_b32_e64 v72, v74, v72, s[10:11]
	v_lshl_add_u64 v[74:75], v[72:73], 0, v[144:145]
	v_lshl_add_u64 v[72:73], v[74:75], 0, s[58:59]
	s_mov_b64 s[10:11], -1
	global_store_dwordx4 v[74:75], v[68:71], off offset:512 sc1
	s_cbranch_execz .LBB0_230
	s_branch .LBB0_233
.LBB0_228:
	global_store_dwordx4 v[86:87], v[72:75], off offset:16 sc1
	s_or_b64 exec, exec, s[70:71]
	s_and_b64 vcc, exec, s[6:7]
	s_cbranch_vccz .LBB0_227

.LBB0_230:
	v_lshlrev_b32_e32 v144, 1, v158
	v_pk_mul_f32 v[70:71], v[70:71], s[56:57] op_sel_hi:[1,0]
	v_pk_mul_f32 v[68:69], v[68:69], s[56:57] op_sel_hi:[1,0]
	v_pk_mul_f32 v[66:67], v[66:67], s[56:57] op_sel_hi:[1,0]
	v_pk_mul_f32 v[64:65], v[64:65], s[56:57] op_sel_hi:[1,0]
	v_cvt_pk_bf16_f32 v72, v68, v69
	v_cvt_pk_bf16_f32 v73, v70, v71
	v_lshl_add_u64 v[76:77], v[84:85], 0, v[144:145]
	v_cvt_pk_bf16_f32 v74, v64, v65
	v_cvt_pk_bf16_f32 v75, v66, v67
	global_store_dwordx4 v[76:77], v[72:75], off offset:256 nt
	s_and_saveexec_b64 s[68:69], s[8:9]
	s_cbranch_execz .LBB0_232
	v_lshl_add_u64 v[72:73], s[44:45], 0, v[80:81]
	v_lshlrev_b32_e32 v144, 2, v158
	v_lshl_add_u64 v[74:75], v[72:73], 0, v[144:145]
	v_lshl_add_u64 v[72:73], v[74:75], 0, s[58:59]
	s_or_b64 s[10:11], s[10:11], exec
	global_store_dwordx4 v[74:75], v[68:71], off offset:512 sc1

.LBB0_233:
	s_and_b64 exec, exec, s[10:11]
	s_cbranch_execz .LBB0_235
	global_store_dwordx4 v[72:73], v[64:67], off offset:16 sc1
.LBB0_235:
	s_or_b64 exec, exec, s[66:67]
	v_cmp_gt_i32_e32 vcc, s87, v156
	s_and_saveexec_b64 s[66:67], vcc
	s_cbranch_execz .LBB0_252
	v_add_u32_e32 v68, 0x80, v156
	v_ashrrev_i32_e32 v69, 31, v68
	s_movk_i32 s8, 0x3f80
	v_add_u32_e32 v144, 0xffffc080, v156
	v_lshlrev_b64 v[66:67], 9, v[68:69]
	v_cmp_gt_i32_e64 s[10:11], s8, v156
	v_lshlrev_b64 v[64:65], 11, v[144:145]
	s_and_b64 vcc, exec, s[6:7]
	v_cmp_lt_i32_e64 s[8:9], s31, v156
	s_cbranch_vccnz .LBB0_238
	s_and_b64 s[68:69], s[64:65], exec
	s_cselect_b32 s25, s89, s91
	s_cselect_b32 s68, s88, s90
	v_mov_b32_e32 v74, s68
	v_mov_b32_e32 v75, s25
	s_lshl_b32 s25, s24, 2
	v_lshl_add_u64 v[74:75], v[66:67], 1, v[74:75]
	v_lshlrev_b32_e32 v144, 1, v158
	s_add_u32 s68, s16, s25
	v_cvt_pk_bf16_f32 v70, v60, v61
	v_cvt_pk_bf16_f32 v71, v62, v63
	v_lshl_add_u64 v[74:75], v[74:75], 0, v[144:145]
	s_addc_u32 s69, s17, 0
	s_lshl_b32 s25, s72, 2
	v_cvt_pk_bf16_f32 v72, v56, v57
	v_cvt_pk_bf16_f32 v73, v58, v59
	global_store_dwordx4 v[74:75], v[70:73], off nt
	v_lshlrev_b32_e32 v144, 2, v158
	s_nop 0
	v_lshl_add_u64 v[70:71], v[66:67], 2, s[68:69]
	s_add_u32 s68, s16, s25
	s_addc_u32 s69, s17, 0
	v_lshl_add_u64 v[72:73], s[68:69], 0, v[64:65]
	v_cndmask_b32_e64 v71, v73, v71, s[10:11]
	v_cndmask_b32_e64 v70, v72, v70, s[10:11]
	v_lshl_add_u64 v[70:71], v[70:71], 0, v[144:145]
	s_mov_b64 s[68:69], -1
	global_store_dwordx4 v[70:71], v[60:63], off sc1
	v_lshlrev_b64 v[68:69], 10, v[68:69]
	v_lshl_add_u64 v[68:69], s[40:41], 0, v[68:69]
	s_cbranch_execz .LBB0_239
	s_branch .LBB0_242

.LBB0_239:
	v_lshlrev_b32_e32 v144, 1, v158
	v_pk_mul_f32 v[62:63], v[62:63], s[56:57] op_sel_hi:[1,0]
	v_pk_mul_f32 v[60:61], v[60:61], s[56:57] op_sel_hi:[1,0]
	v_pk_mul_f32 v[58:59], v[58:59], s[56:57] op_sel_hi:[1,0]
	v_pk_mul_f32 v[56:57], v[56:57], s[56:57] op_sel_hi:[1,0]
	v_cvt_pk_bf16_f32 v70, v60, v61
	v_cvt_pk_bf16_f32 v71, v62, v63
	v_lshl_add_u64 v[74:75], v[68:69], 0, v[144:145]
	v_cvt_pk_bf16_f32 v72, v56, v57
	v_cvt_pk_bf16_f32 v73, v58, v59
	global_store_dwordx4 v[74:75], v[70:73], off nt
	s_and_saveexec_b64 s[70:71], s[8:9]
	s_cbranch_execz .LBB0_241
	v_lshl_add_u64 v[70:71], s[44:45], 0, v[64:65]
	v_lshlrev_b32_e32 v144, 2, v158
	v_lshl_add_u64 v[70:71], v[70:71], 0, v[144:145]
	s_or_b64 s[68:69], s[68:69], exec
	global_store_dwordx4 v[70:71], v[60:63], off sc1

.LBB0_244:
	s_and_b64 s[68:69], s[64:65], exec
	s_cselect_b32 s25, s89, s91
	s_cselect_b32 s68, s88, s90
	v_mov_b32_e32 v60, s68
	v_mov_b32_e32 v61, s25
	s_lshl_b32 s25, s24, 2
	v_lshl_add_u64 v[60:61], v[66:67], 1, v[60:61]
	v_lshlrev_b32_e32 v144, 1, v158
	s_add_u32 s68, s16, s25
	v_cvt_pk_bf16_f32 v56, v52, v53
	v_cvt_pk_bf16_f32 v57, v54, v55
	v_lshl_add_u64 v[60:61], v[60:61], 0, v[144:145]
	s_addc_u32 s69, s17, 0
	s_lshl_b32 s25, s72, 2
	v_cvt_pk_bf16_f32 v58, v48, v49
	v_cvt_pk_bf16_f32 v59, v50, v51
	global_store_dwordx4 v[60:61], v[56:59], off offset:256 nt
	v_lshlrev_b32_e32 v144, 2, v158
	s_nop 0
	v_lshl_add_u64 v[56:57], v[66:67], 2, s[68:69]
	s_add_u32 s68, s16, s25
	s_addc_u32 s69, s17, 0
	v_lshl_add_u64 v[58:59], s[68:69], 0, v[64:65]
	v_cndmask_b32_e64 v57, v59, v57, s[10:11]
	v_cndmask_b32_e64 v56, v58, v56, s[10:11]
	v_lshl_add_u64 v[58:59], v[56:57], 0, v[144:145]
	v_lshl_add_u64 v[56:57], v[58:59], 0, s[58:59]
	s_mov_b64 s[10:11], -1
	global_store_dwordx4 v[58:59], v[52:55], off offset:512 sc1
	s_cbranch_execz .LBB0_247
	s_branch .LBB0_250
.LBB0_245:
	global_store_dwordx4 v[70:71], v[56:59], off offset:16 sc1
	s_or_b64 exec, exec, s[70:71]
	s_and_b64 vcc, exec, s[6:7]
	s_cbranch_vccz .LBB0_244

.LBB0_247:
	v_lshlrev_b32_e32 v144, 1, v158
	v_pk_mul_f32 v[54:55], v[54:55], s[56:57] op_sel_hi:[1,0]
	v_pk_mul_f32 v[52:53], v[52:53], s[56:57] op_sel_hi:[1,0]
	v_pk_mul_f32 v[50:51], v[50:51], s[56:57] op_sel_hi:[1,0]
	v_pk_mul_f32 v[48:49], v[48:49], s[56:57] op_sel_hi:[1,0]
	v_cvt_pk_bf16_f32 v56, v52, v53
	v_cvt_pk_bf16_f32 v57, v54, v55
	v_lshl_add_u64 v[60:61], v[68:69], 0, v[144:145]
	v_cvt_pk_bf16_f32 v58, v48, v49
	v_cvt_pk_bf16_f32 v59, v50, v51
	global_store_dwordx4 v[60:61], v[56:59], off offset:256 nt
	s_and_saveexec_b64 s[68:69], s[8:9]
	s_cbranch_execz .LBB0_249
	v_lshl_add_u64 v[56:57], s[44:45], 0, v[64:65]
	v_lshlrev_b32_e32 v144, 2, v158
	v_lshl_add_u64 v[58:59], v[56:57], 0, v[144:145]
	v_lshl_add_u64 v[56:57], v[58:59], 0, s[58:59]
	s_or_b64 s[10:11], s[10:11], exec
	global_store_dwordx4 v[58:59], v[52:55], off offset:512 sc1

.LBB0_250:
	s_and_b64 exec, exec, s[10:11]
	s_cbranch_execz .LBB0_252
	global_store_dwordx4 v[56:57], v[48:51], off offset:16 sc1
.LBB0_252:
	s_or_b64 exec, exec, s[66:67]
	v_cmp_gt_i32_e32 vcc, s26, v156
	s_and_saveexec_b64 s[66:67], vcc
	s_cbranch_execz .LBB0_269
	v_add_u32_e32 v52, 0x90, v156
	v_ashrrev_i32_e32 v53, 31, v52
	s_movk_i32 s8, 0x3f70
	v_add_u32_e32 v144, 0xffffc090, v156
	v_lshlrev_b64 v[50:51], 9, v[52:53]
	v_cmp_gt_i32_e64 s[10:11], s8, v156
	v_lshlrev_b64 v[48:49], 11, v[144:145]
	s_and_b64 vcc, exec, s[6:7]
	v_cmp_lt_i32_e64 s[8:9], s27, v156
	s_cbranch_vccnz .LBB0_255
	s_and_b64 s[68:69], s[64:65], exec
	s_cselect_b32 s25, s89, s91
	s_cselect_b32 s68, s88, s90
	v_mov_b32_e32 v58, s68
	v_mov_b32_e32 v59, s25
	s_lshl_b32 s25, s24, 2
	v_lshl_add_u64 v[58:59], v[50:51], 1, v[58:59]
	v_lshlrev_b32_e32 v144, 1, v158
	s_add_u32 s68, s16, s25
	v_cvt_pk_bf16_f32 v54, v44, v45
	v_cvt_pk_bf16_f32 v55, v46, v47
	v_lshl_add_u64 v[58:59], v[58:59], 0, v[144:145]
	s_addc_u32 s69, s17, 0
	s_lshl_b32 s25, s72, 2
	v_cvt_pk_bf16_f32 v56, v40, v41
	v_cvt_pk_bf16_f32 v57, v42, v43
	global_store_dwordx4 v[58:59], v[54:57], off nt
	v_lshlrev_b32_e32 v144, 2, v158
	s_nop 0
	v_lshl_add_u64 v[54:55], v[50:51], 2, s[68:69]
	s_add_u32 s68, s16, s25
	s_addc_u32 s69, s17, 0
	v_lshl_add_u64 v[56:57], s[68:69], 0, v[48:49]
	v_cndmask_b32_e64 v55, v57, v55, s[10:11]
	v_cndmask_b32_e64 v54, v56, v54, s[10:11]
	v_lshl_add_u64 v[54:55], v[54:55], 0, v[144:145]
	s_mov_b64 s[68:69], -1
	global_store_dwordx4 v[54:55], v[44:47], off sc1
	v_lshlrev_b64 v[52:53], 10, v[52:53]
	v_lshl_add_u64 v[52:53], s[40:41], 0, v[52:53]
	s_cbranch_execz .LBB0_256
	s_branch .LBB0_259

.LBB0_256:
	v_lshlrev_b32_e32 v144, 1, v158
	v_pk_mul_f32 v[46:47], v[46:47], s[56:57] op_sel_hi:[1,0]
	v_pk_mul_f32 v[44:45], v[44:45], s[56:57] op_sel_hi:[1,0]
	v_pk_mul_f32 v[42:43], v[42:43], s[56:57] op_sel_hi:[1,0]
	v_pk_mul_f32 v[40:41], v[40:41], s[56:57] op_sel_hi:[1,0]
	v_cvt_pk_bf16_f32 v54, v44, v45
	v_cvt_pk_bf16_f32 v55, v46, v47
	v_lshl_add_u64 v[58:59], v[52:53], 0, v[144:145]
	v_cvt_pk_bf16_f32 v56, v40, v41
	v_cvt_pk_bf16_f32 v57, v42, v43
	global_store_dwordx4 v[58:59], v[54:57], off nt
	s_and_saveexec_b64 s[70:71], s[8:9]
	s_cbranch_execz .LBB0_258
	v_lshl_add_u64 v[54:55], s[44:45], 0, v[48:49]
	v_lshlrev_b32_e32 v144, 2, v158
	v_lshl_add_u64 v[54:55], v[54:55], 0, v[144:145]
	s_or_b64 s[68:69], s[68:69], exec
	global_store_dwordx4 v[54:55], v[44:47], off sc1

.LBB0_261:
	s_and_b64 s[68:69], s[64:65], exec
	s_cselect_b32 s25, s89, s91
	s_cselect_b32 s68, s88, s90
	v_mov_b32_e32 v44, s68
	v_mov_b32_e32 v45, s25
	s_lshl_b32 s25, s24, 2
	v_lshl_add_u64 v[44:45], v[50:51], 1, v[44:45]
	v_lshlrev_b32_e32 v144, 1, v158
	s_add_u32 s68, s16, s25
	v_cvt_pk_bf16_f32 v40, v36, v37
	v_cvt_pk_bf16_f32 v41, v38, v39
	v_lshl_add_u64 v[44:45], v[44:45], 0, v[144:145]
	s_addc_u32 s69, s17, 0
	s_lshl_b32 s25, s72, 2
	v_cvt_pk_bf16_f32 v42, v32, v33
	v_cvt_pk_bf16_f32 v43, v34, v35
	global_store_dwordx4 v[44:45], v[40:43], off offset:256 nt
	v_lshlrev_b32_e32 v144, 2, v158
	s_nop 0
	v_lshl_add_u64 v[40:41], v[50:51], 2, s[68:69]
	s_add_u32 s68, s16, s25
	s_addc_u32 s69, s17, 0
	v_lshl_add_u64 v[42:43], s[68:69], 0, v[48:49]
	v_cndmask_b32_e64 v41, v43, v41, s[10:11]
	v_cndmask_b32_e64 v40, v42, v40, s[10:11]
	v_lshl_add_u64 v[42:43], v[40:41], 0, v[144:145]
	v_lshl_add_u64 v[40:41], v[42:43], 0, s[58:59]
	s_mov_b64 s[10:11], -1
	global_store_dwordx4 v[42:43], v[36:39], off offset:512 sc1
	s_cbranch_execz .LBB0_264
	s_branch .LBB0_267
.LBB0_262:
	global_store_dwordx4 v[54:55], v[40:43], off offset:16 sc1
	s_or_b64 exec, exec, s[70:71]
	s_and_b64 vcc, exec, s[6:7]
	s_cbranch_vccz .LBB0_261

.LBB0_264:
	v_lshlrev_b32_e32 v144, 1, v158
	v_pk_mul_f32 v[38:39], v[38:39], s[56:57] op_sel_hi:[1,0]
	v_pk_mul_f32 v[36:37], v[36:37], s[56:57] op_sel_hi:[1,0]
	v_pk_mul_f32 v[34:35], v[34:35], s[56:57] op_sel_hi:[1,0]
	v_pk_mul_f32 v[32:33], v[32:33], s[56:57] op_sel_hi:[1,0]
	v_cvt_pk_bf16_f32 v40, v36, v37
	v_cvt_pk_bf16_f32 v41, v38, v39
	v_lshl_add_u64 v[44:45], v[52:53], 0, v[144:145]
	v_cvt_pk_bf16_f32 v42, v32, v33
	v_cvt_pk_bf16_f32 v43, v34, v35
	global_store_dwordx4 v[44:45], v[40:43], off offset:256 nt
	s_and_saveexec_b64 s[68:69], s[8:9]
	s_cbranch_execz .LBB0_266
	v_lshl_add_u64 v[40:41], s[44:45], 0, v[48:49]
	v_lshlrev_b32_e32 v144, 2, v158
	v_lshl_add_u64 v[42:43], v[40:41], 0, v[144:145]
	v_lshl_add_u64 v[40:41], v[42:43], 0, s[58:59]
	s_or_b64 s[10:11], s[10:11], exec
	global_store_dwordx4 v[42:43], v[36:39], off offset:512 sc1

.LBB0_267:
	s_and_b64 exec, exec, s[10:11]
	s_cbranch_execz .LBB0_269
	global_store_dwordx4 v[40:41], v[32:35], off offset:16 sc1
.LBB0_269:
	s_or_b64 exec, exec, s[66:67]
	v_cmp_gt_i32_e32 vcc, s14, v156
	s_and_saveexec_b64 s[66:67], vcc
	s_cbranch_execz .LBB0_286
	v_add_u32_e32 v36, 0xa0, v156
	v_ashrrev_i32_e32 v37, 31, v36
	s_movk_i32 s8, 0x3f60
	v_add_u32_e32 v144, 0xffffc0a0, v156
	v_lshlrev_b64 v[34:35], 9, v[36:37]
	v_cmp_gt_i32_e64 s[10:11], s8, v156
	v_lshlrev_b64 v[32:33], 11, v[144:145]
	s_and_b64 vcc, exec, s[6:7]
	v_cmp_lt_i32_e64 s[8:9], s15, v156
	s_cbranch_vccnz .LBB0_272
	s_and_b64 s[68:69], s[64:65], exec
	s_cselect_b32 s25, s89, s91
	s_cselect_b32 s68, s88, s90
	v_mov_b32_e32 v42, s68
	v_mov_b32_e32 v43, s25
	s_lshl_b32 s25, s24, 2
	v_lshl_add_u64 v[42:43], v[34:35], 1, v[42:43]
	v_lshlrev_b32_e32 v144, 1, v158
	s_add_u32 s68, s16, s25
	v_cvt_pk_bf16_f32 v38, v28, v29
	v_cvt_pk_bf16_f32 v39, v30, v31
	v_lshl_add_u64 v[42:43], v[42:43], 0, v[144:145]
	s_addc_u32 s69, s17, 0
	s_lshl_b32 s25, s72, 2
	v_cvt_pk_bf16_f32 v40, v24, v25
	v_cvt_pk_bf16_f32 v41, v26, v27
	global_store_dwordx4 v[42:43], v[38:41], off nt
	v_lshlrev_b32_e32 v144, 2, v158
	s_nop 0
	v_lshl_add_u64 v[38:39], v[34:35], 2, s[68:69]
	s_add_u32 s68, s16, s25
	s_addc_u32 s69, s17, 0
	v_lshl_add_u64 v[40:41], s[68:69], 0, v[32:33]
	v_cndmask_b32_e64 v39, v41, v39, s[10:11]
	v_cndmask_b32_e64 v38, v40, v38, s[10:11]
	v_lshl_add_u64 v[38:39], v[38:39], 0, v[144:145]
	s_mov_b64 s[68:69], -1
	global_store_dwordx4 v[38:39], v[28:31], off sc1
	v_lshlrev_b64 v[36:37], 10, v[36:37]
	v_lshl_add_u64 v[36:37], s[40:41], 0, v[36:37]
	s_cbranch_execz .LBB0_273
	s_branch .LBB0_276

.LBB0_273:
	v_lshlrev_b32_e32 v144, 1, v158
	v_pk_mul_f32 v[30:31], v[30:31], s[56:57] op_sel_hi:[1,0]
	v_pk_mul_f32 v[28:29], v[28:29], s[56:57] op_sel_hi:[1,0]
	v_pk_mul_f32 v[26:27], v[26:27], s[56:57] op_sel_hi:[1,0]
	v_pk_mul_f32 v[24:25], v[24:25], s[56:57] op_sel_hi:[1,0]
	v_cvt_pk_bf16_f32 v38, v28, v29
	v_cvt_pk_bf16_f32 v39, v30, v31
	v_lshl_add_u64 v[42:43], v[36:37], 0, v[144:145]
	v_cvt_pk_bf16_f32 v40, v24, v25
	v_cvt_pk_bf16_f32 v41, v26, v27
	global_store_dwordx4 v[42:43], v[38:41], off nt
	s_and_saveexec_b64 s[70:71], s[8:9]
	s_cbranch_execz .LBB0_275
	v_lshl_add_u64 v[38:39], s[44:45], 0, v[32:33]
	v_lshlrev_b32_e32 v144, 2, v158
	v_lshl_add_u64 v[38:39], v[38:39], 0, v[144:145]
	s_or_b64 s[68:69], s[68:69], exec
	global_store_dwordx4 v[38:39], v[28:31], off sc1

.LBB0_278:
	s_and_b64 s[68:69], s[64:65], exec
	s_cselect_b32 s25, s89, s91
	s_cselect_b32 s68, s88, s90
	v_mov_b32_e32 v28, s68
	v_mov_b32_e32 v29, s25
	s_lshl_b32 s25, s24, 2
	v_lshl_add_u64 v[28:29], v[34:35], 1, v[28:29]
	v_lshlrev_b32_e32 v144, 1, v158
	s_add_u32 s68, s16, s25
	v_cvt_pk_bf16_f32 v24, v20, v21
	v_cvt_pk_bf16_f32 v25, v22, v23
	v_lshl_add_u64 v[28:29], v[28:29], 0, v[144:145]
	s_addc_u32 s69, s17, 0
	s_lshl_b32 s25, s72, 2
	v_cvt_pk_bf16_f32 v26, v16, v17
	v_cvt_pk_bf16_f32 v27, v18, v19
	global_store_dwordx4 v[28:29], v[24:27], off offset:256 nt
	v_lshlrev_b32_e32 v144, 2, v158
	s_nop 0
	v_lshl_add_u64 v[24:25], v[34:35], 2, s[68:69]
	s_add_u32 s68, s16, s25
	s_addc_u32 s69, s17, 0
	v_lshl_add_u64 v[26:27], s[68:69], 0, v[32:33]
	v_cndmask_b32_e64 v25, v27, v25, s[10:11]
	v_cndmask_b32_e64 v24, v26, v24, s[10:11]
	v_lshl_add_u64 v[26:27], v[24:25], 0, v[144:145]
	v_lshl_add_u64 v[24:25], v[26:27], 0, s[58:59]
	s_mov_b64 s[10:11], -1
	global_store_dwordx4 v[26:27], v[20:23], off offset:512 sc1
	s_cbranch_execz .LBB0_281
	s_branch .LBB0_284
.LBB0_279:
	global_store_dwordx4 v[38:39], v[24:27], off offset:16 sc1
	s_or_b64 exec, exec, s[70:71]
	s_and_b64 vcc, exec, s[6:7]
	s_cbranch_vccz .LBB0_278

.LBB0_281:
	v_lshlrev_b32_e32 v144, 1, v158
	v_pk_mul_f32 v[22:23], v[22:23], s[56:57] op_sel_hi:[1,0]
	v_pk_mul_f32 v[20:21], v[20:21], s[56:57] op_sel_hi:[1,0]
	v_pk_mul_f32 v[18:19], v[18:19], s[56:57] op_sel_hi:[1,0]
	v_pk_mul_f32 v[16:17], v[16:17], s[56:57] op_sel_hi:[1,0]
	v_cvt_pk_bf16_f32 v24, v20, v21
	v_cvt_pk_bf16_f32 v25, v22, v23
	v_lshl_add_u64 v[28:29], v[36:37], 0, v[144:145]
	v_cvt_pk_bf16_f32 v26, v16, v17
	v_cvt_pk_bf16_f32 v27, v18, v19
	global_store_dwordx4 v[28:29], v[24:27], off offset:256 nt
	s_and_saveexec_b64 s[68:69], s[8:9]
	s_cbranch_execz .LBB0_283
	v_lshl_add_u64 v[24:25], s[44:45], 0, v[32:33]
	v_lshlrev_b32_e32 v144, 2, v158
	v_lshl_add_u64 v[26:27], v[24:25], 0, v[144:145]
	v_lshl_add_u64 v[24:25], v[26:27], 0, s[58:59]
	s_or_b64 s[10:11], s[10:11], exec
	global_store_dwordx4 v[26:27], v[20:23], off offset:512 sc1

.LBB0_284:
	s_and_b64 exec, exec, s[10:11]
	s_cbranch_execz .LBB0_286
	global_store_dwordx4 v[24:25], v[16:19], off offset:16 sc1
.LBB0_286:
	s_or_b64 exec, exec, s[66:67]
	v_cmp_gt_i32_e32 vcc, s81, v156
	s_and_saveexec_b64 s[66:67], vcc
	s_cbranch_execz .LBB0_303
	v_add_u32_e32 v22, 0xb0, v156
	v_ashrrev_i32_e32 v23, 31, v22
	s_movk_i32 s8, 0x3f50
	v_add_u32_e32 v144, 0xffffc0b0, v156
	v_lshlrev_b64 v[20:21], 9, v[22:23]
	v_cmp_gt_i32_e64 s[10:11], s8, v156
	v_lshlrev_b64 v[16:17], 11, v[144:145]
	v_cmp_lt_i32_e64 s[8:9], s80, v156
	s_and_b64 vcc, exec, s[6:7]
	v_lshlrev_b32_e32 v144, 1, v158
	v_lshlrev_b32_e32 v18, 2, v158
	s_cbranch_vccnz .LBB0_289
	s_and_b64 s[68:69], s[64:65], exec
	s_cselect_b32 s25, s89, s91
	s_cselect_b32 s68, s88, s90
	v_mov_b32_e32 v28, s68
	v_mov_b32_e32 v29, s25
	s_lshl_b32 s25, s24, 2
	v_lshl_add_u64 v[28:29], v[20:21], 1, v[28:29]
	s_add_u32 s68, s16, s25
	v_cvt_pk_bf16_f32 v24, v12, v13
	v_cvt_pk_bf16_f32 v25, v14, v15
	v_lshl_add_u64 v[28:29], v[28:29], 0, v[144:145]
	s_addc_u32 s69, s17, 0
	s_lshl_b32 s25, s72, 2
	v_cvt_pk_bf16_f32 v26, v8, v9
	v_cvt_pk_bf16_f32 v27, v10, v11
	global_store_dwordx4 v[28:29], v[24:27], off nt
	v_mov_b32_e32 v19, v145
	s_nop 0
	v_lshl_add_u64 v[24:25], v[20:21], 2, s[68:69]
	s_add_u32 s68, s16, s25
	s_addc_u32 s69, s17, 0
	v_lshl_add_u64 v[26:27], s[68:69], 0, v[16:17]
	v_cndmask_b32_e64 v25, v27, v25, s[10:11]
	v_cndmask_b32_e64 v24, v26, v24, s[10:11]
	v_lshl_add_u64 v[24:25], v[24:25], 0, v[18:19]
	s_mov_b64 s[68:69], -1
	global_store_dwordx4 v[24:25], v[12:15], off sc1
	v_lshlrev_b64 v[22:23], 10, v[22:23]
	v_lshl_add_u64 v[22:23], s[40:41], 0, v[22:23]
	s_cbranch_execz .LBB0_290
	s_branch .LBB0_293

.LBB0_290:
	v_pk_mul_f32 v[14:15], v[14:15], s[56:57] op_sel_hi:[1,0]
	v_pk_mul_f32 v[12:13], v[12:13], s[56:57] op_sel_hi:[1,0]
	v_pk_mul_f32 v[10:11], v[10:11], s[56:57] op_sel_hi:[1,0]
	v_pk_mul_f32 v[8:9], v[8:9], s[56:57] op_sel_hi:[1,0]
	v_cvt_pk_bf16_f32 v24, v12, v13
	v_cvt_pk_bf16_f32 v25, v14, v15
	v_lshl_add_u64 v[28:29], v[22:23], 0, v[144:145]
	v_cvt_pk_bf16_f32 v26, v8, v9
	v_cvt_pk_bf16_f32 v27, v10, v11
	global_store_dwordx4 v[28:29], v[24:27], off nt
	s_and_saveexec_b64 s[70:71], s[8:9]
	s_cbranch_execz .LBB0_292
	v_lshl_add_u64 v[24:25], s[44:45], 0, v[16:17]
	v_mov_b32_e32 v19, v145
	v_lshl_add_u64 v[24:25], v[24:25], 0, v[18:19]
	s_or_b64 s[68:69], s[68:69], exec
	global_store_dwordx4 v[24:25], v[12:15], off sc1

.LBB0_295:
	s_and_b64 s[6:7], s[64:65], exec
	s_cselect_b32 s6, s89, s91
	s_cselect_b32 s7, s88, s90
	v_mov_b32_e32 v12, s7
	v_mov_b32_e32 v13, s6
	s_lshl_b32 s6, s24, 2
	v_lshl_add_u64 v[12:13], v[20:21], 1, v[12:13]
	s_add_u32 s6, s16, s6
	v_cvt_pk_bf16_f32 v8, v4, v5
	v_cvt_pk_bf16_f32 v9, v6, v7
	v_lshl_add_u64 v[12:13], v[12:13], 0, v[144:145]
	s_addc_u32 s7, s17, 0
	v_cvt_pk_bf16_f32 v10, v0, v1
	v_cvt_pk_bf16_f32 v11, v2, v3
	global_store_dwordx4 v[12:13], v[8:11], off offset:256 nt
	v_mov_b32_e32 v19, v145
	s_nop 0
	v_lshl_add_u64 v[8:9], v[20:21], 2, s[6:7]
	s_lshl_b32 s6, s72, 2
	s_add_u32 s6, s16, s6
	s_addc_u32 s7, s17, 0
	v_lshl_add_u64 v[10:11], s[6:7], 0, v[16:17]
	v_cndmask_b32_e64 v9, v11, v9, s[10:11]
	v_cndmask_b32_e64 v8, v10, v8, s[10:11]
	v_lshl_add_u64 v[10:11], v[8:9], 0, v[18:19]
	v_lshl_add_u64 v[8:9], v[10:11], 0, s[58:59]
	s_mov_b64 s[6:7], -1
	global_store_dwordx4 v[10:11], v[4:7], off offset:512 sc1
	s_cbranch_execz .LBB0_300
	s_and_b64 exec, exec, s[6:7]
	s_cbranch_execz .LBB0_303
.LBB0_297:
	global_store_dwordx4 v[8:9], v[0:3], off offset:16 sc1
	s_or_b64 exec, exec, s[66:67]
	s_and_b64 vcc, exec, s[4:5]
	s_mov_b64 s[4:5], -1
	s_cbranch_vccnz .LBB0_98
	s_branch .LBB0_304
.LBB0_298:
	global_store_dwordx4 v[24:25], v[8:11], off offset:16 sc1
	s_or_b64 exec, exec, s[70:71]
	s_and_b64 vcc, exec, s[6:7]
	s_cbranch_vccz .LBB0_295

.LBB0_300:
	s_nop 0
	v_pk_mul_f32 v[6:7], v[6:7], s[56:57] op_sel_hi:[1,0]
	v_pk_mul_f32 v[4:5], v[4:5], s[56:57] op_sel_hi:[1,0]
	v_pk_mul_f32 v[2:3], v[2:3], s[56:57] op_sel_hi:[1,0]
	v_pk_mul_f32 v[0:1], v[0:1], s[56:57] op_sel_hi:[1,0]
	v_cvt_pk_bf16_f32 v8, v4, v5
	v_cvt_pk_bf16_f32 v9, v6, v7
	v_lshl_add_u64 v[12:13], v[22:23], 0, v[144:145]
	v_cvt_pk_bf16_f32 v10, v0, v1
	v_cvt_pk_bf16_f32 v11, v2, v3
	global_store_dwordx4 v[12:13], v[8:11], off offset:256 nt
	s_and_saveexec_b64 s[10:11], s[8:9]
	s_cbranch_execz .LBB0_302
	v_lshl_add_u64 v[8:9], s[44:45], 0, v[16:17]
	v_mov_b32_e32 v19, v145
	v_lshl_add_u64 v[10:11], v[8:9], 0, v[18:19]
	v_lshl_add_u64 v[8:9], v[10:11], 0, s[58:59]
	s_or_b64 s[6:7], s[6:7], exec
	global_store_dwordx4 v[10:11], v[4:7], off offset:512 sc1

.LBB0_315:
	v_lshl_add_u64 v[60:61], v[26:27], 0, s[6:7]
	v_lshl_add_u64 v[62:63], v[24:25], 0, s[6:7]
	v_lshl_add_u64 v[64:65], v[22:23], 0, s[6:7]
	v_lshl_add_u64 v[66:67], v[20:21], 0, s[6:7]
	v_lshl_add_u64 v[68:69], v[18:19], 0, s[6:7]
	v_lshl_add_u64 v[70:71], v[16:17], 0, s[6:7]
	v_lshl_add_u64 v[72:73], v[14:15], 0, s[6:7]
	v_lshl_add_u64 v[74:75], v[12:13], 0, s[6:7]
	global_load_dword v59, v[60:61], off nt
	global_load_dword v76, v[62:63], off nt
	global_load_dword v77, v[64:65], off nt
	global_load_dword v78, v[66:67], off nt
	global_load_dword v79, v[68:69], off nt
	global_load_dword v80, v[70:71], off nt
	global_load_dword v81, v[72:73], off nt
	global_load_dword v82, v[74:75], off nt
	s_add_u32 s6, s6, 0x10000
	s_addc_u32 s7, s7, 0
	v_add_u32_e32 v60, 0x400, v58
	s_cmp_lg_u32 s6, 0x40000
	s_waitcnt vmcnt(0)
	ds_write2_b32 v58, v59, v76 offset1:66
	ds_write2_b32 v58, v77, v78 offset0:132 offset1:198
	ds_write2_b32 v60, v79, v80 offset0:8 offset1:74
	ds_write2_b32 v60, v81, v82 offset0:140 offset1:206
	v_add_u32_e32 v58, 0x840, v58
	s_cbranch_scc1 .LBB0_315
	s_waitcnt lgkmcnt(0)
	ds_read2_b32 v[16:17], v30 offset1:8
	ds_read2_b32 v[20:21], v30 offset0:33 offset1:41
	ds_read2_b32 v[22:23], v30 offset0:66 offset1:74
	ds_read2_b32 v[24:25], v30 offset0:99 offset1:107
	ds_read2_b32 v[26:27], v30 offset0:132 offset1:140
	s_waitcnt lgkmcnt(4)
	v_bfe_u32 v12, v16, 16, 1
	v_add3_u32 v12, v16, v12, s22
	s_waitcnt lgkmcnt(3)
	v_bfe_u32 v13, v20, 16, 1
	v_lshrrev_b32_e32 v12, 16, v12
	v_add3_u32 v13, v20, v13, s22
	ds_read2_b32 v[58:59], v30 offset0:165 offset1:173
	v_and_or_b32 v12, v13, s23, v12
	s_waitcnt lgkmcnt(3)
	v_bfe_u32 v13, v22, 16, 1
	v_add3_u32 v13, v22, v13, s22
	s_waitcnt lgkmcnt(2)
	v_bfe_u32 v14, v24, 16, 1
	ds_read2_b32 v[60:61], v30 offset0:198 offset1:206
	v_lshrrev_b32_e32 v13, 16, v13
	v_add3_u32 v14, v24, v14, s22
	ds_read2_b32 v[62:63], v30 offset0:231 offset1:239
	v_and_or_b32 v13, v14, s23, v13
	s_waitcnt lgkmcnt(3)
	v_bfe_u32 v14, v26, 16, 1
	v_add3_u32 v14, v26, v14, s22
	s_waitcnt lgkmcnt(2)
	v_bfe_u32 v15, v58, 16, 1
	v_lshrrev_b32_e32 v14, 16, v14
	v_add3_u32 v15, v58, v15, s22
	v_and_or_b32 v14, v15, s23, v14
	s_waitcnt lgkmcnt(1)
	v_bfe_u32 v15, v60, 16, 1
	v_add3_u32 v15, v60, v15, s22
	s_waitcnt lgkmcnt(0)
	v_bfe_u32 v16, v62, 16, 1
	s_and_b32 s4, s24, 0x7fffffc0
	v_lshrrev_b32_e32 v15, 16, v15
	v_add3_u32 v16, v62, v16, s22
	s_addk_i32 s4, 0xdc00
	v_and_or_b32 v15, v16, s23, v15
	v_or_b32_e32 v16, s9, v29
	v_lshl_add_u64 v[18:19], s[4:5], 1, v[2:3]
	v_lshlrev_b32_e32 v64, 11, v16
	v_mov_b32_e32 v65, v1
	v_lshl_add_u64 v[64:65], v[18:19], 0, v[64:65]
	global_store_dwordx4 v[64:65], v[12:15], off sc1
	v_bfe_u32 v16, v63, 16, 1
	v_add3_u32 v16, v63, v16, s22
	v_bfe_u32 v12, v17, 16, 1
	v_add3_u32 v12, v17, v12, s22
	v_bfe_u32 v13, v21, 16, 1
	v_lshrrev_b32_e32 v12, 16, v12
	v_add3_u32 v13, v21, v13, s22
	v_and_or_b32 v12, v13, s23, v12
	v_bfe_u32 v13, v23, 16, 1
	v_add3_u32 v13, v23, v13, s22
	v_bfe_u32 v14, v25, 16, 1
	v_lshrrev_b32_e32 v13, 16, v13
	v_add3_u32 v14, v25, v14, s22
	v_and_or_b32 v13, v14, s23, v13
	v_bfe_u32 v14, v27, 16, 1
	v_add3_u32 v14, v27, v14, s22
	v_bfe_u32 v15, v59, 16, 1
	v_lshrrev_b32_e32 v14, 16, v14
	v_add3_u32 v15, v59, v15, s22
	v_and_or_b32 v14, v15, s23, v14
	v_bfe_u32 v15, v61, 16, 1
	v_add3_u32 v15, v61, v15, s22
	v_lshrrev_b32_e32 v15, 16, v15
	v_and_or_b32 v15, v16, s23, v15
	v_or_b32_e32 v16, s9, v31
	v_lshlrev_b32_e32 v16, 11, v16
	v_mov_b32_e32 v17, v1
	ds_read2_b32 v[20:21], v30 offset0:16 offset1:24
	v_lshl_add_u64 v[16:17], v[18:19], 0, v[16:17]
	global_store_dwordx4 v[16:17], v[12:15], off sc1
	ds_read2_b32 v[16:17], v30 offset0:49 offset1:57
	ds_read2_b32 v[22:23], v30 offset0:82 offset1:90
	ds_read2_b32 v[24:25], v30 offset0:115 offset1:123
	s_waitcnt lgkmcnt(3)
	v_bfe_u32 v12, v20, 16, 1
	v_add3_u32 v12, v20, v12, s22
	s_waitcnt lgkmcnt(2)
	v_bfe_u32 v13, v16, 16, 1
	ds_read2_b32 v[26:27], v30 offset0:148 offset1:156
	v_lshrrev_b32_e32 v12, 16, v12
	v_add3_u32 v13, v16, v13, s22
	ds_read2_b32 v[58:59], v30 offset0:181 offset1:189
	v_and_or_b32 v12, v13, s23, v12
	s_waitcnt lgkmcnt(3)
	v_bfe_u32 v13, v22, 16, 1
	v_add3_u32 v13, v22, v13, s22
	s_waitcnt lgkmcnt(2)
	v_bfe_u32 v14, v24, 16, 1
	ds_read2_b32 v[60:61], v30 offset0:214 offset1:222
	v_lshrrev_b32_e32 v13, 16, v13
	v_add3_u32 v14, v24, v14, s22
	ds_read2_b32 v[62:63], v30 offset0:247 offset1:255
	v_and_or_b32 v13, v14, s23, v13
	s_waitcnt lgkmcnt(3)
	v_bfe_u32 v14, v26, 16, 1
	v_add3_u32 v14, v26, v14, s22
	s_waitcnt lgkmcnt(2)
	v_bfe_u32 v15, v58, 16, 1
	v_lshrrev_b32_e32 v14, 16, v14
	v_add3_u32 v15, v58, v15, s22
	v_and_or_b32 v14, v15, s23, v14
	s_waitcnt lgkmcnt(1)
	v_bfe_u32 v15, v60, 16, 1
	v_add3_u32 v15, v60, v15, s22
	s_waitcnt lgkmcnt(0)
	v_bfe_u32 v16, v62, 16, 1
	v_lshrrev_b32_e32 v15, 16, v15
	v_add3_u32 v16, v62, v16, s22
	v_and_or_b32 v15, v16, s23, v15
	v_or_b32_e32 v16, s9, v32
	v_lshlrev_b32_e32 v64, 11, v16
	v_mov_b32_e32 v65, v1
	v_lshl_add_u64 v[64:65], v[18:19], 0, v[64:65]
	global_store_dwordx4 v[64:65], v[12:15], off sc1
	v_bfe_u32 v16, v63, 16, 1
	v_add3_u32 v16, v63, v16, s22
	v_bfe_u32 v12, v21, 16, 1
	v_add3_u32 v12, v21, v12, s22
	v_bfe_u32 v13, v17, 16, 1
	v_lshrrev_b32_e32 v12, 16, v12
	v_add3_u32 v13, v17, v13, s22
	v_and_or_b32 v12, v13, s23, v12
	v_bfe_u32 v13, v23, 16, 1
	v_add3_u32 v13, v23, v13, s22
	v_bfe_u32 v14, v25, 16, 1
	v_lshrrev_b32_e32 v13, 16, v13
	v_add3_u32 v14, v25, v14, s22
	v_and_or_b32 v13, v14, s23, v13
	v_bfe_u32 v14, v27, 16, 1
	v_add3_u32 v14, v27, v14, s22
	v_bfe_u32 v15, v59, 16, 1
	v_lshrrev_b32_e32 v14, 16, v14
	v_add3_u32 v15, v59, v15, s22
	v_and_or_b32 v14, v15, s23, v14
	v_bfe_u32 v15, v61, 16, 1
	v_add3_u32 v15, v61, v15, s22
	v_lshrrev_b32_e32 v15, 16, v15
	v_and_or_b32 v15, v16, s23, v15
	v_or_b32_e32 v16, s9, v33
	v_lshlrev_b32_e32 v16, 11, v16
	v_mov_b32_e32 v17, v1
	v_lshl_add_u64 v[16:17], v[18:19], 0, v[16:17]
	global_store_dwordx4 v[16:17], v[12:15], off sc1
	s_waitcnt lgkmcnt(0)
	s_mov_b64 s[6:7], 0

.LBB0_319:
	v_lshl_add_u64 v[60:61], v[26:27], 0, s[6:7]
	v_lshl_add_u64 v[62:63], v[24:25], 0, s[6:7]
	v_lshl_add_u64 v[64:65], v[22:23], 0, s[6:7]
	v_lshl_add_u64 v[66:67], v[20:21], 0, s[6:7]
	v_lshl_add_u64 v[68:69], v[18:19], 0, s[6:7]
	v_lshl_add_u64 v[70:71], v[16:17], 0, s[6:7]
	v_lshl_add_u64 v[72:73], v[14:15], 0, s[6:7]
	v_lshl_add_u64 v[74:75], v[12:13], 0, s[6:7]
	global_load_dword v59, v[60:61], off nt
	global_load_dword v76, v[62:63], off nt
	global_load_dword v77, v[64:65], off nt
	global_load_dword v78, v[66:67], off nt
	global_load_dword v79, v[68:69], off nt
	global_load_dword v80, v[70:71], off nt
	global_load_dword v81, v[72:73], off nt
	global_load_dword v82, v[74:75], off nt
	s_add_u32 s6, s6, 0x10000
	s_addc_u32 s7, s7, 0
	v_add_u32_e32 v60, 0x400, v58
	s_cmp_lg_u32 s6, 0x40000
	s_waitcnt vmcnt(0)
	ds_write2_b32 v58, v59, v76 offset1:66
	ds_write2_b32 v58, v77, v78 offset0:132 offset1:198
	ds_write2_b32 v60, v79, v80 offset0:8 offset1:74
	ds_write2_b32 v60, v81, v82 offset0:140 offset1:206
	v_add_u32_e32 v58, 0x840, v58
	s_cbranch_scc1 .LBB0_319
	s_waitcnt lgkmcnt(0)
	ds_read2_b32 v[16:17], v30 offset1:8
	ds_read2_b32 v[20:21], v30 offset0:33 offset1:41
	ds_read2_b32 v[22:23], v30 offset0:66 offset1:74
	ds_read2_b32 v[24:25], v30 offset0:99 offset1:107
	ds_read2_b32 v[26:27], v30 offset0:132 offset1:140
	s_waitcnt lgkmcnt(4)
	v_bfe_u32 v12, v16, 16, 1
	v_add3_u32 v12, v16, v12, s22
	s_waitcnt lgkmcnt(3)
	v_bfe_u32 v13, v20, 16, 1
	v_lshrrev_b32_e32 v12, 16, v12
	v_add3_u32 v13, v20, v13, s22
	ds_read2_b32 v[58:59], v30 offset0:165 offset1:173
	v_and_or_b32 v12, v13, s23, v12
	s_waitcnt lgkmcnt(3)
	v_bfe_u32 v13, v22, 16, 1
	v_add3_u32 v13, v22, v13, s22
	s_waitcnt lgkmcnt(2)
	v_bfe_u32 v14, v24, 16, 1
	ds_read2_b32 v[60:61], v30 offset0:198 offset1:206
	v_lshrrev_b32_e32 v13, 16, v13
	v_add3_u32 v14, v24, v14, s22
	ds_read2_b32 v[62:63], v30 offset0:231 offset1:239
	v_and_or_b32 v13, v14, s23, v13
	s_waitcnt lgkmcnt(3)
	v_bfe_u32 v14, v26, 16, 1
	v_add3_u32 v14, v26, v14, s22
	s_waitcnt lgkmcnt(2)
	v_bfe_u32 v15, v58, 16, 1
	v_lshrrev_b32_e32 v14, 16, v14
	v_add3_u32 v15, v58, v15, s22
	v_and_or_b32 v14, v15, s23, v14
	s_waitcnt lgkmcnt(1)
	v_bfe_u32 v15, v60, 16, 1
	v_add3_u32 v15, v60, v15, s22
	s_waitcnt lgkmcnt(0)
	v_bfe_u32 v16, v62, 16, 1
	s_and_b32 s4, s24, 0x3fc0
	v_lshrrev_b32_e32 v15, 16, v15
	v_add3_u32 v16, v62, v16, s22
	s_addk_i32 s4, 0xec00
	v_and_or_b32 v15, v16, s23, v15
	v_or_b32_e32 v16, s9, v29
	v_lshl_add_u64 v[18:19], s[4:5], 1, v[4:5]
	v_lshlrev_b32_e32 v64, 13, v16
	v_mov_b32_e32 v65, v1
	v_lshl_add_u64 v[64:65], v[18:19], 0, v[64:65]
	global_store_dwordx4 v[64:65], v[12:15], off sc1
	v_bfe_u32 v16, v63, 16, 1
	v_add3_u32 v16, v63, v16, s22
	v_bfe_u32 v12, v17, 16, 1
	v_add3_u32 v12, v17, v12, s22
	v_bfe_u32 v13, v21, 16, 1
	v_lshrrev_b32_e32 v12, 16, v12
	v_add3_u32 v13, v21, v13, s22
	v_and_or_b32 v12, v13, s23, v12
	v_bfe_u32 v13, v23, 16, 1
	v_add3_u32 v13, v23, v13, s22
	v_bfe_u32 v14, v25, 16, 1
	v_lshrrev_b32_e32 v13, 16, v13
	v_add3_u32 v14, v25, v14, s22
	v_and_or_b32 v13, v14, s23, v13
	v_bfe_u32 v14, v27, 16, 1
	v_add3_u32 v14, v27, v14, s22
	v_bfe_u32 v15, v59, 16, 1
	v_lshrrev_b32_e32 v14, 16, v14
	v_add3_u32 v15, v59, v15, s22
	v_and_or_b32 v14, v15, s23, v14
	v_bfe_u32 v15, v61, 16, 1
	v_add3_u32 v15, v61, v15, s22
	v_lshrrev_b32_e32 v15, 16, v15
	v_and_or_b32 v15, v16, s23, v15
	v_or_b32_e32 v16, s9, v31
	v_lshlrev_b32_e32 v16, 13, v16
	v_mov_b32_e32 v17, v1
	ds_read2_b32 v[20:21], v30 offset0:16 offset1:24
	v_lshl_add_u64 v[16:17], v[18:19], 0, v[16:17]
	global_store_dwordx4 v[16:17], v[12:15], off sc1
	ds_read2_b32 v[16:17], v30 offset0:49 offset1:57
	ds_read2_b32 v[22:23], v30 offset0:82 offset1:90
	ds_read2_b32 v[24:25], v30 offset0:115 offset1:123
	s_waitcnt lgkmcnt(3)
	v_bfe_u32 v12, v20, 16, 1
	v_add3_u32 v12, v20, v12, s22
	s_waitcnt lgkmcnt(2)
	v_bfe_u32 v13, v16, 16, 1
	ds_read2_b32 v[26:27], v30 offset0:148 offset1:156
	v_lshrrev_b32_e32 v12, 16, v12
	v_add3_u32 v13, v16, v13, s22
	ds_read2_b32 v[58:59], v30 offset0:181 offset1:189
	v_and_or_b32 v12, v13, s23, v12
	s_waitcnt lgkmcnt(3)
	v_bfe_u32 v13, v22, 16, 1
	v_add3_u32 v13, v22, v13, s22
	s_waitcnt lgkmcnt(2)
	v_bfe_u32 v14, v24, 16, 1
	ds_read2_b32 v[60:61], v30 offset0:214 offset1:222
	v_lshrrev_b32_e32 v13, 16, v13
	v_add3_u32 v14, v24, v14, s22
	ds_read2_b32 v[62:63], v30 offset0:247 offset1:255
	v_and_or_b32 v13, v14, s23, v13
	s_waitcnt lgkmcnt(3)
	v_bfe_u32 v14, v26, 16, 1
	v_add3_u32 v14, v26, v14, s22
	s_waitcnt lgkmcnt(2)
	v_bfe_u32 v15, v58, 16, 1
	v_lshrrev_b32_e32 v14, 16, v14
	v_add3_u32 v15, v58, v15, s22
	v_and_or_b32 v14, v15, s23, v14
	s_waitcnt lgkmcnt(1)
	v_bfe_u32 v15, v60, 16, 1
	v_add3_u32 v15, v60, v15, s22
	s_waitcnt lgkmcnt(0)
	v_bfe_u32 v16, v62, 16, 1
	v_lshrrev_b32_e32 v15, 16, v15
	v_add3_u32 v16, v62, v16, s22
	v_and_or_b32 v15, v16, s23, v15
	v_or_b32_e32 v16, s9, v32
	v_lshlrev_b32_e32 v64, 13, v16
	v_mov_b32_e32 v65, v1
	v_lshl_add_u64 v[64:65], v[18:19], 0, v[64:65]
	global_store_dwordx4 v[64:65], v[12:15], off sc1
	v_bfe_u32 v16, v63, 16, 1
	v_add3_u32 v16, v63, v16, s22
	v_bfe_u32 v12, v21, 16, 1
	v_add3_u32 v12, v21, v12, s22
	v_bfe_u32 v13, v17, 16, 1
	v_lshrrev_b32_e32 v12, 16, v12
	v_add3_u32 v13, v17, v13, s22
	v_and_or_b32 v12, v13, s23, v12
	v_bfe_u32 v13, v23, 16, 1
	v_add3_u32 v13, v23, v13, s22
	v_bfe_u32 v14, v25, 16, 1
	v_lshrrev_b32_e32 v13, 16, v13
	v_add3_u32 v14, v25, v14, s22
	v_and_or_b32 v13, v14, s23, v13
	v_bfe_u32 v14, v27, 16, 1
	v_add3_u32 v14, v27, v14, s22
	v_bfe_u32 v15, v59, 16, 1
	v_lshrrev_b32_e32 v14, 16, v14
	v_add3_u32 v15, v59, v15, s22
	v_and_or_b32 v14, v15, s23, v14
	v_bfe_u32 v15, v61, 16, 1
	v_add3_u32 v15, v61, v15, s22
	v_lshrrev_b32_e32 v15, 16, v15
	v_and_or_b32 v15, v16, s23, v15
	v_or_b32_e32 v16, s9, v33
	v_lshlrev_b32_e32 v16, 13, v16
	v_mov_b32_e32 v17, v1
	v_lshl_add_u64 v[16:17], v[18:19], 0, v[16:17]
	global_store_dwordx4 v[16:17], v[12:15], off sc1
	s_waitcnt lgkmcnt(0)

.LBB0_324:
	v_lshl_add_u64 v[60:61], v[26:27], 0, s[6:7]
	v_lshl_add_u64 v[62:63], v[24:25], 0, s[6:7]
	v_lshl_add_u64 v[64:65], v[22:23], 0, s[6:7]
	v_lshl_add_u64 v[66:67], v[20:21], 0, s[6:7]
	v_lshl_add_u64 v[68:69], v[18:19], 0, s[6:7]
	v_lshl_add_u64 v[70:71], v[16:17], 0, s[6:7]
	v_lshl_add_u64 v[72:73], v[14:15], 0, s[6:7]
	v_lshl_add_u64 v[74:75], v[12:13], 0, s[6:7]
	global_load_dword v59, v[60:61], off nt
	global_load_dword v76, v[62:63], off nt
	global_load_dword v77, v[64:65], off nt
	global_load_dword v78, v[66:67], off nt
	global_load_dword v79, v[68:69], off nt
	global_load_dword v80, v[70:71], off nt
	global_load_dword v81, v[72:73], off nt
	global_load_dword v82, v[74:75], off nt
	s_add_u32 s6, s6, 0x40000
	s_addc_u32 s7, s7, 0
	v_add_u32_e32 v60, 0x400, v58
	s_cmp_lg_u32 s6, 0x100000
	s_waitcnt vmcnt(0)
	ds_write2_b32 v58, v59, v76 offset1:66
	ds_write2_b32 v58, v77, v78 offset0:132 offset1:198
	ds_write2_b32 v60, v79, v80 offset0:8 offset1:74
	ds_write2_b32 v60, v81, v82 offset0:140 offset1:206
	v_add_u32_e32 v58, 0x840, v58
	s_cbranch_scc1 .LBB0_324
	s_waitcnt lgkmcnt(0)
	ds_read2_b32 v[16:17], v30 offset1:8
	ds_read2_b32 v[20:21], v30 offset0:33 offset1:41
	ds_read2_b32 v[22:23], v30 offset0:66 offset1:74
	ds_read2_b32 v[24:25], v30 offset0:99 offset1:107
	ds_read2_b32 v[26:27], v30 offset0:132 offset1:140
	s_waitcnt lgkmcnt(4)
	v_bfe_u32 v12, v16, 16, 1
	v_add3_u32 v12, v16, v12, s22
	s_waitcnt lgkmcnt(3)
	v_bfe_u32 v13, v20, 16, 1
	v_lshrrev_b32_e32 v12, 16, v12
	v_add3_u32 v13, v20, v13, s22
	ds_read2_b32 v[58:59], v30 offset0:165 offset1:173
	v_and_or_b32 v12, v13, s23, v12
	s_waitcnt lgkmcnt(3)
	v_bfe_u32 v13, v22, 16, 1
	v_add3_u32 v13, v22, v13, s22
	s_waitcnt lgkmcnt(2)
	v_bfe_u32 v14, v24, 16, 1
	ds_read2_b32 v[60:61], v30 offset0:198 offset1:206
	v_lshrrev_b32_e32 v13, 16, v13
	v_add3_u32 v14, v24, v14, s22
	ds_read2_b32 v[62:63], v30 offset0:231 offset1:239
	v_and_or_b32 v13, v14, s23, v13
	s_waitcnt lgkmcnt(3)
	v_bfe_u32 v14, v26, 16, 1
	v_add3_u32 v14, v26, v14, s22
	s_waitcnt lgkmcnt(2)
	v_bfe_u32 v15, v58, 16, 1
	v_lshrrev_b32_e32 v14, 16, v14
	v_add3_u32 v15, v58, v15, s22
	v_and_or_b32 v14, v15, s23, v14
	s_waitcnt lgkmcnt(1)
	v_bfe_u32 v15, v60, 16, 1
	s_lshl_b32 s6, s10, 5
	v_add3_u32 v15, v60, v15, s22
	s_waitcnt lgkmcnt(0)
	v_bfe_u32 v16, v62, 16, 1
	s_add_i32 s4, s10, 0xfffffe00
	s_and_b32 s6, s6, 0xfe0
	v_lshrrev_b32_e32 v15, 16, v15
	v_add3_u32 v16, v62, v16, s22
	s_and_b32 s4, s4, 0xffffff80
	v_and_or_b32 v15, v16, s23, v15
	v_or_b32_e32 v16, s6, v29
	v_lshl_add_u64 v[18:19], v[6:7], 0, s[4:5]
	v_lshlrev_b32_e32 v64, 11, v16
	v_mov_b32_e32 v65, v1
	v_lshl_add_u64 v[64:65], v[18:19], 0, v[64:65]
	global_store_dwordx4 v[64:65], v[12:15], off sc1
	v_bfe_u32 v16, v63, 16, 1
	v_add3_u32 v16, v63, v16, s22
	v_bfe_u32 v12, v17, 16, 1
	v_add3_u32 v12, v17, v12, s22
	v_bfe_u32 v13, v21, 16, 1
	v_lshrrev_b32_e32 v12, 16, v12
	v_add3_u32 v13, v21, v13, s22
	v_and_or_b32 v12, v13, s23, v12
	v_bfe_u32 v13, v23, 16, 1
	v_add3_u32 v13, v23, v13, s22
	v_bfe_u32 v14, v25, 16, 1
	v_lshrrev_b32_e32 v13, 16, v13
	v_add3_u32 v14, v25, v14, s22
	v_and_or_b32 v13, v14, s23, v13
	v_bfe_u32 v14, v27, 16, 1
	v_add3_u32 v14, v27, v14, s22
	v_bfe_u32 v15, v59, 16, 1
	v_lshrrev_b32_e32 v14, 16, v14
	v_add3_u32 v15, v59, v15, s22
	v_and_or_b32 v14, v15, s23, v14
	v_bfe_u32 v15, v61, 16, 1
	v_add3_u32 v15, v61, v15, s22
	v_lshrrev_b32_e32 v15, 16, v15
	v_and_or_b32 v15, v16, s23, v15
	v_or_b32_e32 v16, s6, v31
	v_lshlrev_b32_e32 v16, 11, v16
	v_mov_b32_e32 v17, v1
	ds_read2_b32 v[20:21], v30 offset0:16 offset1:24
	v_lshl_add_u64 v[16:17], v[18:19], 0, v[16:17]
	global_store_dwordx4 v[16:17], v[12:15], off sc1
	ds_read2_b32 v[16:17], v30 offset0:49 offset1:57
	ds_read2_b32 v[22:23], v30 offset0:82 offset1:90
	ds_read2_b32 v[24:25], v30 offset0:115 offset1:123
	s_waitcnt lgkmcnt(3)
	v_bfe_u32 v12, v20, 16, 1
	v_add3_u32 v12, v20, v12, s22
	s_waitcnt lgkmcnt(2)
	v_bfe_u32 v13, v16, 16, 1
	ds_read2_b32 v[26:27], v30 offset0:148 offset1:156
	v_lshrrev_b32_e32 v12, 16, v12
	v_add3_u32 v13, v16, v13, s22
	ds_read2_b32 v[58:59], v30 offset0:181 offset1:189
	v_and_or_b32 v12, v13, s23, v12
	s_waitcnt lgkmcnt(3)
	v_bfe_u32 v13, v22, 16, 1
	v_add3_u32 v13, v22, v13, s22
	s_waitcnt lgkmcnt(2)
	v_bfe_u32 v14, v24, 16, 1
	ds_read2_b32 v[60:61], v30 offset0:214 offset1:222
	v_lshrrev_b32_e32 v13, 16, v13
	v_add3_u32 v14, v24, v14, s22
	ds_read2_b32 v[62:63], v30 offset0:247 offset1:255
	v_and_or_b32 v13, v14, s23, v13
	s_waitcnt lgkmcnt(3)
	v_bfe_u32 v14, v26, 16, 1
	v_add3_u32 v14, v26, v14, s22
	s_waitcnt lgkmcnt(2)
	v_bfe_u32 v15, v58, 16, 1
	v_lshrrev_b32_e32 v14, 16, v14
	v_add3_u32 v15, v58, v15, s22
	v_and_or_b32 v14, v15, s23, v14
	s_waitcnt lgkmcnt(1)
	v_bfe_u32 v15, v60, 16, 1
	v_add3_u32 v15, v60, v15, s22
	s_waitcnt lgkmcnt(0)
	v_bfe_u32 v16, v62, 16, 1
	v_lshrrev_b32_e32 v15, 16, v15
	v_add3_u32 v16, v62, v16, s22
	v_and_or_b32 v15, v16, s23, v15
	v_or_b32_e32 v16, s6, v32
	v_lshlrev_b32_e32 v64, 11, v16
	v_mov_b32_e32 v65, v1
	v_lshl_add_u64 v[64:65], v[18:19], 0, v[64:65]
	global_store_dwordx4 v[64:65], v[12:15], off sc1
	v_bfe_u32 v16, v63, 16, 1
	v_add3_u32 v16, v63, v16, s22
	v_bfe_u32 v12, v21, 16, 1
	v_add3_u32 v12, v21, v12, s22
	v_bfe_u32 v13, v17, 16, 1
	v_lshrrev_b32_e32 v12, 16, v12
	v_add3_u32 v13, v17, v13, s22
	v_and_or_b32 v12, v13, s23, v12
	v_bfe_u32 v13, v23, 16, 1
	v_add3_u32 v13, v23, v13, s22
	v_bfe_u32 v14, v25, 16, 1
	v_lshrrev_b32_e32 v13, 16, v13
	v_add3_u32 v14, v25, v14, s22
	v_and_or_b32 v13, v14, s23, v13
	v_bfe_u32 v14, v27, 16, 1
	v_add3_u32 v14, v27, v14, s22
	v_bfe_u32 v15, v59, 16, 1
	v_lshrrev_b32_e32 v14, 16, v14
	v_add3_u32 v15, v59, v15, s22
	v_and_or_b32 v14, v15, s23, v14
	v_bfe_u32 v15, v61, 16, 1
	v_add3_u32 v15, v61, v15, s22
	v_lshrrev_b32_e32 v15, 16, v15
	v_and_or_b32 v15, v16, s23, v15
	v_or_b32_e32 v16, s6, v33
	v_lshlrev_b32_e32 v16, 11, v16
	v_mov_b32_e32 v17, v1
	v_lshl_add_u64 v[16:17], v[18:19], 0, v[16:17]
	global_store_dwordx4 v[16:17], v[12:15], off sc1
	s_waitcnt lgkmcnt(0)

.LBB0_329:
	v_add_u32_e32 v16, s4, v14
	v_ashrrev_i32_e32 v17, 31, v16
	v_add_u32_e32 v18, 2, v16
	v_add_u32_e32 v20, 4, v16
	v_add_u32_e32 v22, 6, v16
	v_add_u32_e32 v24, 8, v16
	v_add_u32_e32 v26, 10, v16
	v_add_u32_e32 v58, 12, v16
	v_add_u32_e32 v60, 14, v16
	v_lshlrev_b64 v[16:17], 12, v[16:17]
	v_ashrrev_i32_e32 v19, 31, v18
	v_ashrrev_i32_e32 v21, 31, v20
	v_ashrrev_i32_e32 v23, 31, v22
	v_ashrrev_i32_e32 v25, 31, v24
	v_ashrrev_i32_e32 v27, 31, v26
	v_ashrrev_i32_e32 v59, 31, v58
	v_ashrrev_i32_e32 v61, 31, v60
	v_lshl_add_u64 v[16:17], v[12:13], 0, v[16:17]
	v_lshlrev_b64 v[18:19], 12, v[18:19]
	v_lshlrev_b64 v[20:21], 12, v[20:21]
	v_lshlrev_b64 v[22:23], 12, v[22:23]
	v_lshlrev_b64 v[24:25], 12, v[24:25]
	v_lshlrev_b64 v[26:27], 12, v[26:27]
	v_lshlrev_b64 v[58:59], 12, v[58:59]
	v_lshlrev_b64 v[60:61], 12, v[60:61]
	v_lshl_add_u64 v[18:19], v[12:13], 0, v[18:19]
	v_lshl_add_u64 v[20:21], v[12:13], 0, v[20:21]
	v_lshl_add_u64 v[22:23], v[12:13], 0, v[22:23]
	v_lshl_add_u64 v[24:25], v[12:13], 0, v[24:25]
	v_lshl_add_u64 v[26:27], v[12:13], 0, v[26:27]
	v_lshl_add_u64 v[58:59], v[12:13], 0, v[58:59]
	v_lshl_add_u64 v[60:61], v[12:13], 0, v[60:61]
	global_load_dword v62, v[16:17], off nt
	global_load_dword v63, v[18:19], off nt
	global_load_dword v64, v[20:21], off nt
	global_load_dword v65, v[22:23], off nt
	global_load_dword v66, v[24:25], off nt
	global_load_dword v67, v[26:27], off nt
	global_load_dword v68, v[58:59], off nt
	global_load_dword v69, v[60:61], off nt
	s_add_i32 s4, s4, 16
	v_add_u32_e32 v16, 0x400, v15
	s_cmp_lg_u32 s4, 64
	s_waitcnt vmcnt(0)
	ds_write2_b32 v15, v62, v63 offset1:66
	ds_write2_b32 v15, v64, v65 offset0:132 offset1:198
	ds_write2_b32 v16, v66, v67 offset0:8 offset1:74
	ds_write2_b32 v16, v68, v69 offset0:140 offset1:206
	v_add_u32_e32 v15, 0x840, v15
	s_cbranch_scc1 .LBB0_329
	s_waitcnt lgkmcnt(0)
	ds_read2_b32 v[16:17], v30 offset1:8
	ds_read2_b32 v[20:21], v30 offset0:33 offset1:41
	ds_read2_b32 v[22:23], v30 offset0:66 offset1:74
	ds_read2_b32 v[24:25], v30 offset0:99 offset1:107
	ds_read2_b32 v[26:27], v30 offset0:132 offset1:140
	ds_read2_b32 v[58:59], v30 offset0:165 offset1:173
	s_waitcnt lgkmcnt(5)
	v_bfe_u32 v12, v16, 16, 1
	v_add3_u32 v12, v16, v12, s22
	s_waitcnt lgkmcnt(4)
	v_bfe_u32 v13, v20, 16, 1
	v_lshrrev_b32_e32 v12, 16, v12
	v_add3_u32 v13, v20, v13, s22
	v_and_or_b32 v12, v13, s23, v12
	s_waitcnt lgkmcnt(3)
	v_bfe_u32 v13, v22, 16, 1
	v_add3_u32 v13, v22, v13, s22
	s_waitcnt lgkmcnt(2)
	v_bfe_u32 v14, v24, 16, 1
	ds_read2_b32 v[60:61], v30 offset0:198 offset1:206
	v_lshrrev_b32_e32 v13, 16, v13
	v_add3_u32 v14, v24, v14, s22
	ds_read2_b32 v[62:63], v30 offset0:231 offset1:239
	v_and_or_b32 v13, v14, s23, v13
	s_waitcnt lgkmcnt(3)
	v_bfe_u32 v14, v26, 16, 1
	v_add3_u32 v14, v26, v14, s22
	s_waitcnt lgkmcnt(2)
	v_bfe_u32 v15, v58, 16, 1
	v_lshrrev_b32_e32 v14, 16, v14
	v_add3_u32 v15, v58, v15, s22
	v_and_or_b32 v14, v15, s23, v14
	s_waitcnt lgkmcnt(1)
	v_bfe_u32 v15, v60, 16, 1
	v_or_b32_e32 v64, s6, v29
	s_ashr_i32 s9, s8, 31
	v_add3_u32 v15, v60, v15, s22
	s_waitcnt lgkmcnt(0)
	v_bfe_u32 v16, v62, 16, 1
	v_ashrrev_i32_e32 v65, 31, v64
	v_lshl_add_u64 v[18:19], s[8:9], 1, v[8:9]
	v_lshrrev_b32_e32 v15, 16, v15
	v_add3_u32 v16, v62, v16, s22
	v_lshlrev_b64 v[64:65], 11, v[64:65]
	v_and_or_b32 v15, v16, s23, v15
	v_lshl_add_u64 v[64:65], v[18:19], 0, v[64:65]
	global_store_dwordx4 v[64:65], v[12:15], off sc1
	v_bfe_u32 v16, v63, 16, 1
	v_add3_u32 v16, v63, v16, s22
	v_bfe_u32 v12, v17, 16, 1
	v_add3_u32 v12, v17, v12, s22
	v_bfe_u32 v13, v21, 16, 1
	v_lshrrev_b32_e32 v12, 16, v12
	v_add3_u32 v13, v21, v13, s22
	v_and_or_b32 v12, v13, s23, v12
	v_bfe_u32 v13, v23, 16, 1
	v_add3_u32 v13, v23, v13, s22
	v_bfe_u32 v14, v25, 16, 1
	v_lshrrev_b32_e32 v13, 16, v13
	v_add3_u32 v14, v25, v14, s22
	v_and_or_b32 v13, v14, s23, v13
	v_bfe_u32 v14, v27, 16, 1
	v_add3_u32 v14, v27, v14, s22
	v_bfe_u32 v15, v59, 16, 1
	v_lshrrev_b32_e32 v14, 16, v14
	v_add3_u32 v15, v59, v15, s22
	v_and_or_b32 v14, v15, s23, v14
	v_bfe_u32 v15, v61, 16, 1
	v_add3_u32 v15, v61, v15, s22
	v_lshrrev_b32_e32 v15, 16, v15
	v_and_or_b32 v15, v16, s23, v15
	v_or_b32_e32 v16, s6, v31
	v_ashrrev_i32_e32 v17, 31, v16
	v_lshlrev_b64 v[16:17], 11, v[16:17]
	ds_read2_b32 v[20:21], v30 offset0:16 offset1:24
	v_lshl_add_u64 v[16:17], v[18:19], 0, v[16:17]
	global_store_dwordx4 v[16:17], v[12:15], off sc1
	ds_read2_b32 v[16:17], v30 offset0:49 offset1:57
	ds_read2_b32 v[22:23], v30 offset0:82 offset1:90
	ds_read2_b32 v[24:25], v30 offset0:115 offset1:123
	s_waitcnt lgkmcnt(3)
	v_bfe_u32 v12, v20, 16, 1
	v_add3_u32 v12, v20, v12, s22
	s_waitcnt lgkmcnt(2)
	v_bfe_u32 v13, v16, 16, 1
	ds_read2_b32 v[26:27], v30 offset0:148 offset1:156
	v_lshrrev_b32_e32 v12, 16, v12
	v_add3_u32 v13, v16, v13, s22
	ds_read2_b32 v[58:59], v30 offset0:181 offset1:189
	v_and_or_b32 v12, v13, s23, v12
	s_waitcnt lgkmcnt(3)
	v_bfe_u32 v13, v22, 16, 1
	v_add3_u32 v13, v22, v13, s22
	s_waitcnt lgkmcnt(2)
	v_bfe_u32 v14, v24, 16, 1
	ds_read2_b32 v[60:61], v30 offset0:214 offset1:222
	v_lshrrev_b32_e32 v13, 16, v13
	v_add3_u32 v14, v24, v14, s22
	ds_read2_b32 v[62:63], v30 offset0:247 offset1:255
	v_and_or_b32 v13, v14, s23, v13
	s_waitcnt lgkmcnt(3)
	v_bfe_u32 v14, v26, 16, 1
	v_add3_u32 v14, v26, v14, s22
	s_waitcnt lgkmcnt(2)
	v_bfe_u32 v15, v58, 16, 1
	v_lshrrev_b32_e32 v14, 16, v14
	v_add3_u32 v15, v58, v15, s22
	v_and_or_b32 v14, v15, s23, v14
	s_waitcnt lgkmcnt(1)
	v_bfe_u32 v15, v60, 16, 1
	v_or_b32_e32 v64, s6, v32
	v_add3_u32 v15, v60, v15, s22
	s_waitcnt lgkmcnt(0)
	v_bfe_u32 v16, v62, 16, 1
	v_ashrrev_i32_e32 v65, 31, v64
	v_lshrrev_b32_e32 v15, 16, v15
	v_add3_u32 v16, v62, v16, s22
	v_lshlrev_b64 v[64:65], 11, v[64:65]
	v_and_or_b32 v15, v16, s23, v15
	v_lshl_add_u64 v[64:65], v[18:19], 0, v[64:65]
	global_store_dwordx4 v[64:65], v[12:15], off sc1
	v_bfe_u32 v16, v63, 16, 1
	v_add3_u32 v16, v63, v16, s22
	v_bfe_u32 v12, v21, 16, 1
	v_add3_u32 v12, v21, v12, s22
	v_bfe_u32 v13, v17, 16, 1
	v_lshrrev_b32_e32 v12, 16, v12
	v_add3_u32 v13, v17, v13, s22
	v_and_or_b32 v12, v13, s23, v12
	v_bfe_u32 v13, v23, 16, 1
	v_add3_u32 v13, v23, v13, s22
	v_bfe_u32 v14, v25, 16, 1
	v_lshrrev_b32_e32 v13, 16, v13
	v_add3_u32 v14, v25, v14, s22
	v_and_or_b32 v13, v14, s23, v13
	v_bfe_u32 v14, v27, 16, 1
	v_add3_u32 v14, v27, v14, s22
	v_bfe_u32 v15, v59, 16, 1
	v_lshrrev_b32_e32 v14, 16, v14
	v_add3_u32 v15, v59, v15, s22
	v_and_or_b32 v14, v15, s23, v14
	v_bfe_u32 v15, v61, 16, 1
	v_add3_u32 v15, v61, v15, s22
	v_lshrrev_b32_e32 v15, 16, v15
	v_and_or_b32 v15, v16, s23, v15
	v_or_b32_e32 v16, s6, v33
	v_ashrrev_i32_e32 v17, 31, v16
	v_lshlrev_b64 v[16:17], 11, v[16:17]
	v_lshl_add_u64 v[16:17], v[18:19], 0, v[16:17]
	global_store_dwordx4 v[16:17], v[12:15], off sc1
	s_waitcnt lgkmcnt(0)
	s_branch .LBB0_310
